# fast hand-written P1 GEMM epilogue for plain/scale/silu/KV tiles + DPP in thin tiles and fused norm
# speedup vs baseline: 1.0110x; 1.0002x over previous
; DI v4u pack8(f32x4 a, f32x4 b) { v4u w; w.x = cvtpk(a[0], a[1]); w.y = cvtpk(a[2], a[3]); w.z = cvtpk(b[0], b[1]); w.w = cvtpk(b[2], b[3]); return w; }
; DI float silu_f(float z) { return z * __builtin_amdgcn_rcpf(1.f + fexp2(-z * LOG2E)); }
;     DI void operator()(const f32x4 (&acc)[2][2][4][2], const pg8::Unit& u, int wr, int wc, int fr, int fq) const {
;     ...
;         bf16* dst; int ld, c0; float sc = 1.f; int kind = 0;
;         size_t o_p = 0, o_s = 0;
;         if (pn == 0) { dst = CB; ld = 256; c0 = 0; }
;         else if (pn <= 4) { dst = Q; ld = 512; c0 = (pn - 3) * 256; sc = QSCALE; }
;         else if (pn <= 6) { dst = K; ld = 512; c0 = (pn - 5) * 256; kind = 1; o_p = O_PWK; o_s = O_SWK; }
;         else if (pn <= 8) { dst = V; ld = 512; c0 = (pn - 7) * 256; kind = 1; o_p = O_PWV; o_s = O_SWV; }
;         else if (pn == 9) { dst = MQ; ld = 256; c0 = 0; sc = QSCALE; }
;         else if (pn <= 13) { dst = G; ld = 1024; c0 = (pn - 10) * 256; kind = 2; }
;         else { dst = (pn == 14) ? MK : MV; ld = 256; c0 = 0; kind = 3; o_p = (pn == 14) ? O_PMK : O_PMV; }
; #pragma unroll
;         for (int ai = 0; ai < 2; ++ai)
; #pragma unroll
;             for (int m = 0; m < 4; ++m) { const int row = rb + ai * 128 + m * 16;
; #pragma unroll
;                 for (int bj = 0; bj < 2; ++bj) { const int col = c0 + bj * 128 + cl;
;                     f32x4 v0 = acc[ai][bj][m][0], v1 = acc[ai][bj][m][1];
;                     if (kind == 3) { const int mr = row - MT;
;                         *(v4u*)(dst + (size_t)mr * ld + col) = pack8(v0, v1);
;                         float* fo = out + o_p + (size_t)mr * 256 + col; *(f32x4*)fo = v0; *(f32x4*)(fo + 4) = v1; continue; }
;                     if (kind == 1) { float* fo = nullptr;
;                         if (row < MP) { const int t = row & (SEQ - 1); if (t >= SEQ - 2048) fo = out + o_p + ((size_t)((row >> 13) * 2048 + (t - (SEQ - 2048)))) * 512 + col; }
;                         else fo = out + o_s + (size_t)(row - MP) * 512 + col;
;                         if (fo) { *(f32x4*)fo = v0; *(f32x4*)(fo + 4) = v1; } }
;                     if (kind == 2) {
; #pragma unroll
;                         for (int e = 0; e < 4; ++e) { v0[e] = silu_f(v0[e]); v1[e] = silu_f(v1[e]); } }
;                     else { v0 = v0 * sc; v1 = v1 * sc; }
;                     *(v4u*)(dst + (size_t)row * ld + col) = pack8(v0, v1); } }
.LBB0_190:
	s_cmp_eq_u32 s90, 1
	s_cbranch_scc1 .Lep_orig
	s_cmp_eq_u32 s90, 2
	s_cbranch_scc1 .Lep_orig
	s_cmp_gt_u32 s90, 13
	s_cbranch_scc1 .Lep_orig
	v_and_b32_e32 v150, 15, v0
	v_bfe_u32 v151, v0, 4, 2
	v_bfe_u32 v152, v0, 6, 2
	v_lshrrev_b32_e32 v153, 8, v0
	v_lshl_add_u32 v150, v153, 6, v150
	v_lshlrev_b32_e32 v151, 3, v151
	v_lshl_add_u32 v151, v152, 5, v151
	s_lshl_b32 s1, s0, 8
	s_mov_b32 s83, 1.0
	s_mov_b32 s3, 0
	s_cmp_eq_u32 s90, 0
	s_cbranch_scc1 .Lep_cb
	s_cmp_lt_u32 s90, 5
	s_cbranch_scc1 .Lep_q
	s_cmp_lt_u32 s90, 7
	s_cbranch_scc1 .Lep_k
	s_cmp_lt_u32 s90, 9
	s_cbranch_scc1 .Lep_v
	s_cmp_eq_u32 s90, 9
	s_cbranch_scc1 .Lep_mq
	s_mov_b64 s[4:5], s[24:25]
	s_mov_b32 s18, 10
	s_sub_u32 s19, s90, 10
	s_lshl_b32 s19, s19, 8
	s_mov_b32 s3, 2
	s_branch .Lep_addr
.Lep_cb:
	v_readlane_b32 s4, v247, 45
	v_readlane_b32 s5, v247, 46
	s_mov_b32 s18, 8
	s_mov_b32 s19, 0
	s_nop 2
	s_branch .Lep_addr
.Lep_q:
	s_mov_b64 s[4:5], s[78:79]
	s_mov_b32 s18, 9
	s_sub_u32 s19, s90, 3
	s_lshl_b32 s19, s19, 8
	s_mov_b32 s83, 0x3e38aa3b
	s_mov_b32 s3, 1
	s_branch .Lep_addr
.Lep_mq:
	v_readlane_b32 s4, v247, 51
	v_readlane_b32 s5, v247, 52
	s_mov_b32 s18, 8
	s_mov_b32 s19, 0
	s_mov_b32 s83, 0x3e38aa3b
	s_mov_b32 s3, 1
	s_nop 2
	s_branch .Lep_addr
.Lep_k:
	s_mov_b64 s[4:5], s[76:77]
	s_mov_b32 s18, 9
	s_sub_u32 s19, s90, 5
	s_lshl_b32 s19, s19, 8
	s_mov_b32 s94, 0x1080000
	s_mov_b32 s95, 0x14c0400
	s_branch .Lep_kv
.Lep_v:
	s_mov_b64 s[4:5], s[80:81]
	s_mov_b32 s18, 9
	s_sub_u32 s19, s90, 7
	s_lshl_b32 s19, s19, 8
	s_mov_b32 s94, 0x1280000
	s_mov_b32 s95, 0x1500400
.Lep_kv:
	s_cmp_gt_u32 s0, 63
	s_cbranch_scc1 .Lep_kv_s
	s_and_b32 s12, s0, 31
	s_cmp_lt_u32 s12, 24
	s_cbranch_scc1 .Lep_addr
	s_lshr_b32 s16, s0, 5
	s_lshl_b32 s16, s16, 11
	s_sub_u32 s12, s12, 24
	s_lshl_b32 s12, s12, 8
	s_add_u32 s16, s16, s12
	s_lshl_b32 s16, s16, 9
	s_add_u32 s16, s16, s94
	s_branch .Lep_kv_f
.Lep_kv_s:
	s_sub_u32 s16, s0, 64
	s_lshl_b32 s16, s16, 17
	s_add_u32 s16, s16, s95
.Lep_kv_f:
	s_add_u32 s16, s16, s19
	s_lshl_b32 s12, s16, 2
	v_readlane_b32 s16, v247, 39
	v_readlane_b32 s17, v247, 40
	s_mov_b32 s3, 3
	v_lshl_add_u32 v144, v150, 9, v151
	v_lshlrev_b32_e32 v144, 2, v144
	s_add_u32 s16, s16, s12
	s_addc_u32 s17, s17, 0
.Lep_addr:
	s_lshl_b32 s1, s1, s18
	s_add_u32 s1, s1, s19
	s_lshl_b32 s1, s1, 1
	s_add_u32 s4, s4, s1
	s_addc_u32 s5, s5, 0
	v_lshlrev_b32_e32 v152, s18, v150
	v_add_lshl_u32 v152, v152, v151, 1
	s_lshl_b32 s92, 32, s18
	s_lshl_b32 s93, 0x100, s18
	v_mov_b32_e32 v153, v152
	s_cmp_eq_u32 s3, 1
	s_cbranch_scc1 .Lep_scale
	s_cmp_eq_u32 s3, 2
	s_cbranch_scc1 .Lep_silu
	s_cmp_eq_u32 s3, 3
	s_cbranch_scc1 .Lep_plainf
	v_cvt_pk_bf16_f32 v130, v126, v127
	v_cvt_pk_bf16_f32 v131, v128, v129
	v_cvt_pk_bf16_f32 v132, v122, v123
	v_cvt_pk_bf16_f32 v133, v124, v125
	global_store_dwordx4 v153, v[130:133], s[4:5]
	v_cvt_pk_bf16_f32 v154, v118, v119
	v_cvt_pk_bf16_f32 v155, v120, v121
	v_cvt_pk_bf16_f32 v156, v114, v115
	v_cvt_pk_bf16_f32 v157, v116, v117
	global_store_dwordx4 v153, v[154:157], s[4:5] offset:256
	v_add_u32_e32 v153, s92, v153
	v_cvt_pk_bf16_f32 v130, v110, v111
	v_cvt_pk_bf16_f32 v131, v112, v113
	v_cvt_pk_bf16_f32 v132, v106, v107
	v_cvt_pk_bf16_f32 v133, v108, v109
	global_store_dwordx4 v153, v[130:133], s[4:5]
	v_cvt_pk_bf16_f32 v154, v102, v103
	v_cvt_pk_bf16_f32 v155, v104, v105
	v_cvt_pk_bf16_f32 v156, v98, v99
	v_cvt_pk_bf16_f32 v157, v100, v101
	global_store_dwordx4 v153, v[154:157], s[4:5] offset:256
	v_add_u32_e32 v153, s92, v153
	v_cvt_pk_bf16_f32 v130, v94, v95
	v_cvt_pk_bf16_f32 v131, v96, v97
	v_cvt_pk_bf16_f32 v132, v90, v91
	v_cvt_pk_bf16_f32 v133, v92, v93
	global_store_dwordx4 v153, v[130:133], s[4:5]
	v_cvt_pk_bf16_f32 v154, v86, v87
	v_cvt_pk_bf16_f32 v155, v88, v89
	v_cvt_pk_bf16_f32 v156, v82, v83
	v_cvt_pk_bf16_f32 v157, v84, v85
	global_store_dwordx4 v153, v[154:157], s[4:5] offset:256
	v_add_u32_e32 v153, s92, v153
	v_cvt_pk_bf16_f32 v130, v78, v79
	v_cvt_pk_bf16_f32 v131, v80, v81
	v_cvt_pk_bf16_f32 v132, v74, v75
	v_cvt_pk_bf16_f32 v133, v76, v77
	global_store_dwordx4 v153, v[130:133], s[4:5]
	v_cvt_pk_bf16_f32 v154, v70, v71
	v_cvt_pk_bf16_f32 v155, v72, v73
	v_cvt_pk_bf16_f32 v156, v66, v67
	v_cvt_pk_bf16_f32 v157, v68, v69
	global_store_dwordx4 v153, v[154:157], s[4:5] offset:256
	v_add_u32_e32 v153, s93, v152
	v_cvt_pk_bf16_f32 v130, v62, v63
	v_cvt_pk_bf16_f32 v131, v64, v65
	v_cvt_pk_bf16_f32 v132, v58, v59
	v_cvt_pk_bf16_f32 v133, v60, v61
	global_store_dwordx4 v153, v[130:133], s[4:5]
	v_cvt_pk_bf16_f32 v154, v54, v55
	v_cvt_pk_bf16_f32 v155, v56, v57
	v_cvt_pk_bf16_f32 v156, v50, v51
	v_cvt_pk_bf16_f32 v157, v52, v53
	global_store_dwordx4 v153, v[154:157], s[4:5] offset:256
	v_add_u32_e32 v153, s92, v153
	v_cvt_pk_bf16_f32 v130, v46, v47
	v_cvt_pk_bf16_f32 v131, v48, v49
	v_cvt_pk_bf16_f32 v132, v42, v43
	v_cvt_pk_bf16_f32 v133, v44, v45
	global_store_dwordx4 v153, v[130:133], s[4:5]
	v_cvt_pk_bf16_f32 v154, v38, v39
	v_cvt_pk_bf16_f32 v155, v40, v41
	v_cvt_pk_bf16_f32 v156, v34, v35
	v_cvt_pk_bf16_f32 v157, v36, v37
	global_store_dwordx4 v153, v[154:157], s[4:5] offset:256
	v_add_u32_e32 v153, s92, v153
	v_cvt_pk_bf16_f32 v130, v30, v31
	v_cvt_pk_bf16_f32 v131, v32, v33
	v_cvt_pk_bf16_f32 v132, v26, v27
	v_cvt_pk_bf16_f32 v133, v28, v29
	global_store_dwordx4 v153, v[130:133], s[4:5]
	v_cvt_pk_bf16_f32 v154, v22, v23
	v_cvt_pk_bf16_f32 v155, v24, v25
	v_cvt_pk_bf16_f32 v156, v18, v19
	v_cvt_pk_bf16_f32 v157, v20, v21
	global_store_dwordx4 v153, v[154:157], s[4:5] offset:256
	v_add_u32_e32 v153, s92, v153
	v_cvt_pk_bf16_f32 v130, v14, v15
	v_cvt_pk_bf16_f32 v131, v16, v17
	v_cvt_pk_bf16_f32 v132, v10, v11
	v_cvt_pk_bf16_f32 v133, v12, v13
	global_store_dwordx4 v153, v[130:133], s[4:5]
	v_cvt_pk_bf16_f32 v154, v6, v7
	v_cvt_pk_bf16_f32 v155, v8, v9
	v_cvt_pk_bf16_f32 v156, v2, v3
	v_cvt_pk_bf16_f32 v157, v4, v5
	global_store_dwordx4 v153, v[154:157], s[4:5] offset:256
	s_branch .LBB0_374
; DI v4u pack8(f32x4 a, f32x4 b) { v4u w; w.x = cvtpk(a[0], a[1]); w.y = cvtpk(a[2], a[3]); w.z = cvtpk(b[0], b[1]); w.w = cvtpk(b[2], b[3]); return w; }
; DI float silu_f(float z) { return z * __builtin_amdgcn_rcpf(1.f + fexp2(-z * LOG2E)); }
;     DI void operator()(const f32x4 (&acc)[2][2][4][2], const pg8::Unit& u, int wr, int wc, int fr, int fq) const {
;     ...
;                 for (int bj = 0; bj < 2; ++bj) { const int col = c0 + bj * 128 + cl;
;                     f32x4 v0 = acc[ai][bj][m][0], v1 = acc[ai][bj][m][1];
;                     if (kind == 3) { const int mr = row - MT;
;                         *(v4u*)(dst + (size_t)mr * ld + col) = pack8(v0, v1);
;                         float* fo = out + o_p + (size_t)mr * 256 + col; *(f32x4*)fo = v0; *(f32x4*)(fo + 4) = v1; continue; }
;                     if (kind == 1) { float* fo = nullptr;
;                         if (row < MP) { const int t = row & (SEQ - 1); if (t >= SEQ - 2048) fo = out + o_p + ((size_t)((row >> 13) * 2048 + (t - (SEQ - 2048)))) * 512 + col; }
;                         else fo = out + o_s + (size_t)(row - MP) * 512 + col;
;                         if (fo) { *(f32x4*)fo = v0; *(f32x4*)(fo + 4) = v1; } }
;                     if (kind == 2) {
; #pragma unroll
;                         for (int e = 0; e < 4; ++e) { v0[e] = silu_f(v0[e]); v1[e] = silu_f(v1[e]); } }
;                     else { v0 = v0 * sc; v1 = v1 * sc; }
;                     *(v4u*)(dst + (size_t)row * ld + col) = pack8(v0, v1); } }
.Lep_plainf:
	v_cvt_pk_bf16_f32 v130, v126, v127
	v_cvt_pk_bf16_f32 v131, v128, v129
	v_cvt_pk_bf16_f32 v132, v122, v123
	v_cvt_pk_bf16_f32 v133, v124, v125
	global_store_dwordx4 v153, v[130:133], s[4:5]
	global_store_dwordx4 v144, v[126:129], s[16:17]
	global_store_dwordx4 v144, v[122:125], s[16:17] offset:16
	v_cvt_pk_bf16_f32 v154, v118, v119
	v_cvt_pk_bf16_f32 v155, v120, v121
	v_cvt_pk_bf16_f32 v156, v114, v115
	v_cvt_pk_bf16_f32 v157, v116, v117
	global_store_dwordx4 v153, v[154:157], s[4:5] offset:256
	global_store_dwordx4 v144, v[118:121], s[16:17] offset:512
	global_store_dwordx4 v144, v[114:117], s[16:17] offset:528
	v_add_u32_e32 v153, s92, v153
	v_add_u32_e32 v144, 0x8000, v144
	v_cvt_pk_bf16_f32 v130, v110, v111
	v_cvt_pk_bf16_f32 v131, v112, v113
	v_cvt_pk_bf16_f32 v132, v106, v107
	v_cvt_pk_bf16_f32 v133, v108, v109
	global_store_dwordx4 v153, v[130:133], s[4:5]
	global_store_dwordx4 v144, v[110:113], s[16:17]
	global_store_dwordx4 v144, v[106:109], s[16:17] offset:16
	v_cvt_pk_bf16_f32 v154, v102, v103
	v_cvt_pk_bf16_f32 v155, v104, v105
	v_cvt_pk_bf16_f32 v156, v98, v99
	v_cvt_pk_bf16_f32 v157, v100, v101
	global_store_dwordx4 v153, v[154:157], s[4:5] offset:256
	global_store_dwordx4 v144, v[102:105], s[16:17] offset:512
	global_store_dwordx4 v144, v[98:101], s[16:17] offset:528
	v_add_u32_e32 v153, s92, v153
	v_add_u32_e32 v144, 0x8000, v144
	v_cvt_pk_bf16_f32 v130, v94, v95
	v_cvt_pk_bf16_f32 v131, v96, v97
	v_cvt_pk_bf16_f32 v132, v90, v91
	v_cvt_pk_bf16_f32 v133, v92, v93
	global_store_dwordx4 v153, v[130:133], s[4:5]
	global_store_dwordx4 v144, v[94:97], s[16:17]
	global_store_dwordx4 v144, v[90:93], s[16:17] offset:16
	v_cvt_pk_bf16_f32 v154, v86, v87
	v_cvt_pk_bf16_f32 v155, v88, v89
	v_cvt_pk_bf16_f32 v156, v82, v83
	v_cvt_pk_bf16_f32 v157, v84, v85
	global_store_dwordx4 v153, v[154:157], s[4:5] offset:256
	global_store_dwordx4 v144, v[86:89], s[16:17] offset:512
	global_store_dwordx4 v144, v[82:85], s[16:17] offset:528
	v_add_u32_e32 v153, s92, v153
	v_add_u32_e32 v144, 0x8000, v144
	v_cvt_pk_bf16_f32 v130, v78, v79
	v_cvt_pk_bf16_f32 v131, v80, v81
	v_cvt_pk_bf16_f32 v132, v74, v75
	v_cvt_pk_bf16_f32 v133, v76, v77
	global_store_dwordx4 v153, v[130:133], s[4:5]
	global_store_dwordx4 v144, v[78:81], s[16:17]
	global_store_dwordx4 v144, v[74:77], s[16:17] offset:16
	v_cvt_pk_bf16_f32 v154, v70, v71
	v_cvt_pk_bf16_f32 v155, v72, v73
	v_cvt_pk_bf16_f32 v156, v66, v67
	v_cvt_pk_bf16_f32 v157, v68, v69
	global_store_dwordx4 v153, v[154:157], s[4:5] offset:256
	global_store_dwordx4 v144, v[70:73], s[16:17] offset:512
	global_store_dwordx4 v144, v[66:69], s[16:17] offset:528
	v_add_u32_e32 v153, s93, v152
	v_add_u32_e32 v144, 0x28000, v144
	v_cvt_pk_bf16_f32 v130, v62, v63
	v_cvt_pk_bf16_f32 v131, v64, v65
	v_cvt_pk_bf16_f32 v132, v58, v59
	v_cvt_pk_bf16_f32 v133, v60, v61
	global_store_dwordx4 v153, v[130:133], s[4:5]
	global_store_dwordx4 v144, v[62:65], s[16:17]
	global_store_dwordx4 v144, v[58:61], s[16:17] offset:16
	v_cvt_pk_bf16_f32 v154, v54, v55
	v_cvt_pk_bf16_f32 v155, v56, v57
	v_cvt_pk_bf16_f32 v156, v50, v51
	v_cvt_pk_bf16_f32 v157, v52, v53
	global_store_dwordx4 v153, v[154:157], s[4:5] offset:256
	global_store_dwordx4 v144, v[54:57], s[16:17] offset:512
	global_store_dwordx4 v144, v[50:53], s[16:17] offset:528
	v_add_u32_e32 v153, s92, v153
	v_add_u32_e32 v144, 0x8000, v144
	v_cvt_pk_bf16_f32 v130, v46, v47
	v_cvt_pk_bf16_f32 v131, v48, v49
	v_cvt_pk_bf16_f32 v132, v42, v43
	v_cvt_pk_bf16_f32 v133, v44, v45
	global_store_dwordx4 v153, v[130:133], s[4:5]
	global_store_dwordx4 v144, v[46:49], s[16:17]
	global_store_dwordx4 v144, v[42:45], s[16:17] offset:16
	v_cvt_pk_bf16_f32 v154, v38, v39
	v_cvt_pk_bf16_f32 v155, v40, v41
	v_cvt_pk_bf16_f32 v156, v34, v35
	v_cvt_pk_bf16_f32 v157, v36, v37
	global_store_dwordx4 v153, v[154:157], s[4:5] offset:256
	global_store_dwordx4 v144, v[38:41], s[16:17] offset:512
	global_store_dwordx4 v144, v[34:37], s[16:17] offset:528
	v_add_u32_e32 v153, s92, v153
	v_add_u32_e32 v144, 0x8000, v144
	v_cvt_pk_bf16_f32 v130, v30, v31
	v_cvt_pk_bf16_f32 v131, v32, v33
	v_cvt_pk_bf16_f32 v132, v26, v27
	v_cvt_pk_bf16_f32 v133, v28, v29
	global_store_dwordx4 v153, v[130:133], s[4:5]
	global_store_dwordx4 v144, v[30:33], s[16:17]
	global_store_dwordx4 v144, v[26:29], s[16:17] offset:16
	v_cvt_pk_bf16_f32 v154, v22, v23
	v_cvt_pk_bf16_f32 v155, v24, v25
	v_cvt_pk_bf16_f32 v156, v18, v19
	v_cvt_pk_bf16_f32 v157, v20, v21
	global_store_dwordx4 v153, v[154:157], s[4:5] offset:256
	global_store_dwordx4 v144, v[22:25], s[16:17] offset:512
	global_store_dwordx4 v144, v[18:21], s[16:17] offset:528
	v_add_u32_e32 v153, s92, v153
	v_add_u32_e32 v144, 0x8000, v144
	v_cvt_pk_bf16_f32 v130, v14, v15
	v_cvt_pk_bf16_f32 v131, v16, v17
	v_cvt_pk_bf16_f32 v132, v10, v11
	v_cvt_pk_bf16_f32 v133, v12, v13
	global_store_dwordx4 v153, v[130:133], s[4:5]
	global_store_dwordx4 v144, v[14:17], s[16:17]
	global_store_dwordx4 v144, v[10:13], s[16:17] offset:16
	v_cvt_pk_bf16_f32 v154, v6, v7
	v_cvt_pk_bf16_f32 v155, v8, v9
	v_cvt_pk_bf16_f32 v156, v2, v3
	v_cvt_pk_bf16_f32 v157, v4, v5
	global_store_dwordx4 v153, v[154:157], s[4:5] offset:256
	global_store_dwordx4 v144, v[6:9], s[16:17] offset:512
	global_store_dwordx4 v144, v[2:5], s[16:17] offset:528
	s_branch .LBB0_374
; DI v4u pack8(f32x4 a, f32x4 b) { v4u w; w.x = cvtpk(a[0], a[1]); w.y = cvtpk(a[2], a[3]); w.z = cvtpk(b[0], b[1]); w.w = cvtpk(b[2], b[3]); return w; }
; DI float silu_f(float z) { return z * __builtin_amdgcn_rcpf(1.f + fexp2(-z * LOG2E)); }
;     DI void operator()(const f32x4 (&acc)[2][2][4][2], const pg8::Unit& u, int wr, int wc, int fr, int fq) const {
;     ...
; #pragma unroll
;         for (int ai = 0; ai < 2; ++ai)
; #pragma unroll
;             for (int m = 0; m < 4; ++m) { const int row = rb + ai * 128 + m * 16;
; #pragma unroll
;                 for (int bj = 0; bj < 2; ++bj) { const int col = c0 + bj * 128 + cl;
;                     f32x4 v0 = acc[ai][bj][m][0], v1 = acc[ai][bj][m][1];
;                     if (kind == 3) { const int mr = row - MT;
;                         *(v4u*)(dst + (size_t)mr * ld + col) = pack8(v0, v1);
;                         float* fo = out + o_p + (size_t)mr * 256 + col; *(f32x4*)fo = v0; *(f32x4*)(fo + 4) = v1; continue; }
;                     if (kind == 1) { float* fo = nullptr;
;                         if (row < MP) { const int t = row & (SEQ - 1); if (t >= SEQ - 2048) fo = out + o_p + ((size_t)((row >> 13) * 2048 + (t - (SEQ - 2048)))) * 512 + col; }
;                         else fo = out + o_s + (size_t)(row - MP) * 512 + col;
;                         if (fo) { *(f32x4*)fo = v0; *(f32x4*)(fo + 4) = v1; } }
;                     if (kind == 2) {
; #pragma unroll
;                         for (int e = 0; e < 4; ++e) { v0[e] = silu_f(v0[e]); v1[e] = silu_f(v1[e]); } }
;                     else { v0 = v0 * sc; v1 = v1 * sc; }
;                     *(v4u*)(dst + (size_t)row * ld + col) = pack8(v0, v1); } }
.Lep_scale:
	v_mul_f32_e32 v154, s83, v126
	v_mul_f32_e32 v155, s83, v127
	v_mul_f32_e32 v156, s83, v128
	v_mul_f32_e32 v157, s83, v129
	v_mul_f32_e32 v158, s83, v122
	v_mul_f32_e32 v159, s83, v123
	v_mul_f32_e32 v160, s83, v124
	v_mul_f32_e32 v161, s83, v125
	v_cvt_pk_bf16_f32 v130, v154, v155
	v_cvt_pk_bf16_f32 v131, v156, v157
	v_cvt_pk_bf16_f32 v132, v158, v159
	v_cvt_pk_bf16_f32 v133, v160, v161
	global_store_dwordx4 v153, v[130:133], s[4:5]
	v_mul_f32_e32 v154, s83, v118
	v_mul_f32_e32 v155, s83, v119
	v_mul_f32_e32 v156, s83, v120
	v_mul_f32_e32 v157, s83, v121
	v_mul_f32_e32 v158, s83, v114
	v_mul_f32_e32 v159, s83, v115
	v_mul_f32_e32 v160, s83, v116
	v_mul_f32_e32 v161, s83, v117
	v_cvt_pk_bf16_f32 v130, v154, v155
	v_cvt_pk_bf16_f32 v131, v156, v157
	v_cvt_pk_bf16_f32 v132, v158, v159
	v_cvt_pk_bf16_f32 v133, v160, v161
	global_store_dwordx4 v153, v[130:133], s[4:5] offset:256
	v_add_u32_e32 v153, s92, v153
	v_mul_f32_e32 v154, s83, v110
	v_mul_f32_e32 v155, s83, v111
	v_mul_f32_e32 v156, s83, v112
	v_mul_f32_e32 v157, s83, v113
	v_mul_f32_e32 v158, s83, v106
	v_mul_f32_e32 v159, s83, v107
	v_mul_f32_e32 v160, s83, v108
	v_mul_f32_e32 v161, s83, v109
	v_cvt_pk_bf16_f32 v130, v154, v155
	v_cvt_pk_bf16_f32 v131, v156, v157
	v_cvt_pk_bf16_f32 v132, v158, v159
	v_cvt_pk_bf16_f32 v133, v160, v161
	global_store_dwordx4 v153, v[130:133], s[4:5]
	v_mul_f32_e32 v154, s83, v102
	v_mul_f32_e32 v155, s83, v103
	v_mul_f32_e32 v156, s83, v104
	v_mul_f32_e32 v157, s83, v105
	v_mul_f32_e32 v158, s83, v98
	v_mul_f32_e32 v159, s83, v99
	v_mul_f32_e32 v160, s83, v100
	v_mul_f32_e32 v161, s83, v101
	v_cvt_pk_bf16_f32 v130, v154, v155
	v_cvt_pk_bf16_f32 v131, v156, v157
	v_cvt_pk_bf16_f32 v132, v158, v159
	v_cvt_pk_bf16_f32 v133, v160, v161
	global_store_dwordx4 v153, v[130:133], s[4:5] offset:256
	v_add_u32_e32 v153, s92, v153
	v_mul_f32_e32 v154, s83, v94
	v_mul_f32_e32 v155, s83, v95
	v_mul_f32_e32 v156, s83, v96
	v_mul_f32_e32 v157, s83, v97
	v_mul_f32_e32 v158, s83, v90
	v_mul_f32_e32 v159, s83, v91
	v_mul_f32_e32 v160, s83, v92
	v_mul_f32_e32 v161, s83, v93
	v_cvt_pk_bf16_f32 v130, v154, v155
	v_cvt_pk_bf16_f32 v131, v156, v157
	v_cvt_pk_bf16_f32 v132, v158, v159
	v_cvt_pk_bf16_f32 v133, v160, v161
	global_store_dwordx4 v153, v[130:133], s[4:5]
	v_mul_f32_e32 v154, s83, v86
	v_mul_f32_e32 v155, s83, v87
	v_mul_f32_e32 v156, s83, v88
	v_mul_f32_e32 v157, s83, v89
	v_mul_f32_e32 v158, s83, v82
	v_mul_f32_e32 v159, s83, v83
	v_mul_f32_e32 v160, s83, v84
	v_mul_f32_e32 v161, s83, v85
	v_cvt_pk_bf16_f32 v130, v154, v155
	v_cvt_pk_bf16_f32 v131, v156, v157
	v_cvt_pk_bf16_f32 v132, v158, v159
	v_cvt_pk_bf16_f32 v133, v160, v161
	global_store_dwordx4 v153, v[130:133], s[4:5] offset:256
	v_add_u32_e32 v153, s92, v153
	v_mul_f32_e32 v154, s83, v78
	v_mul_f32_e32 v155, s83, v79
	v_mul_f32_e32 v156, s83, v80
	v_mul_f32_e32 v157, s83, v81
	v_mul_f32_e32 v158, s83, v74
	v_mul_f32_e32 v159, s83, v75
	v_mul_f32_e32 v160, s83, v76
	v_mul_f32_e32 v161, s83, v77
	v_cvt_pk_bf16_f32 v130, v154, v155
	v_cvt_pk_bf16_f32 v131, v156, v157
	v_cvt_pk_bf16_f32 v132, v158, v159
	v_cvt_pk_bf16_f32 v133, v160, v161
	global_store_dwordx4 v153, v[130:133], s[4:5]
	v_mul_f32_e32 v154, s83, v70
	v_mul_f32_e32 v155, s83, v71
	v_mul_f32_e32 v156, s83, v72
	v_mul_f32_e32 v157, s83, v73
	v_mul_f32_e32 v158, s83, v66
	v_mul_f32_e32 v159, s83, v67
	v_mul_f32_e32 v160, s83, v68
	v_mul_f32_e32 v161, s83, v69
	v_cvt_pk_bf16_f32 v130, v154, v155
	v_cvt_pk_bf16_f32 v131, v156, v157
	v_cvt_pk_bf16_f32 v132, v158, v159
	v_cvt_pk_bf16_f32 v133, v160, v161
	global_store_dwordx4 v153, v[130:133], s[4:5] offset:256
	v_add_u32_e32 v153, s93, v152
	v_mul_f32_e32 v154, s83, v62
	v_mul_f32_e32 v155, s83, v63
	v_mul_f32_e32 v156, s83, v64
	v_mul_f32_e32 v157, s83, v65
	v_mul_f32_e32 v158, s83, v58
	v_mul_f32_e32 v159, s83, v59
	v_mul_f32_e32 v160, s83, v60
	v_mul_f32_e32 v161, s83, v61
	v_cvt_pk_bf16_f32 v130, v154, v155
	v_cvt_pk_bf16_f32 v131, v156, v157
	v_cvt_pk_bf16_f32 v132, v158, v159
	v_cvt_pk_bf16_f32 v133, v160, v161
	global_store_dwordx4 v153, v[130:133], s[4:5]
	v_mul_f32_e32 v154, s83, v54
	v_mul_f32_e32 v155, s83, v55
	v_mul_f32_e32 v156, s83, v56
	v_mul_f32_e32 v157, s83, v57
	v_mul_f32_e32 v158, s83, v50
	v_mul_f32_e32 v159, s83, v51
	v_mul_f32_e32 v160, s83, v52
	v_mul_f32_e32 v161, s83, v53
	v_cvt_pk_bf16_f32 v130, v154, v155
	v_cvt_pk_bf16_f32 v131, v156, v157
	v_cvt_pk_bf16_f32 v132, v158, v159
	v_cvt_pk_bf16_f32 v133, v160, v161
	global_store_dwordx4 v153, v[130:133], s[4:5] offset:256
	v_add_u32_e32 v153, s92, v153
	v_mul_f32_e32 v154, s83, v46
	v_mul_f32_e32 v155, s83, v47
	v_mul_f32_e32 v156, s83, v48
	v_mul_f32_e32 v157, s83, v49
	v_mul_f32_e32 v158, s83, v42
	v_mul_f32_e32 v159, s83, v43
	v_mul_f32_e32 v160, s83, v44
	v_mul_f32_e32 v161, s83, v45
	v_cvt_pk_bf16_f32 v130, v154, v155
	v_cvt_pk_bf16_f32 v131, v156, v157
	v_cvt_pk_bf16_f32 v132, v158, v159
	v_cvt_pk_bf16_f32 v133, v160, v161
	global_store_dwordx4 v153, v[130:133], s[4:5]
	v_mul_f32_e32 v154, s83, v38
	v_mul_f32_e32 v155, s83, v39
	v_mul_f32_e32 v156, s83, v40
	v_mul_f32_e32 v157, s83, v41
	v_mul_f32_e32 v158, s83, v34
	v_mul_f32_e32 v159, s83, v35
	v_mul_f32_e32 v160, s83, v36
	v_mul_f32_e32 v161, s83, v37
	v_cvt_pk_bf16_f32 v130, v154, v155
	v_cvt_pk_bf16_f32 v131, v156, v157
	v_cvt_pk_bf16_f32 v132, v158, v159
	v_cvt_pk_bf16_f32 v133, v160, v161
	global_store_dwordx4 v153, v[130:133], s[4:5] offset:256
	v_add_u32_e32 v153, s92, v153
	v_mul_f32_e32 v154, s83, v30
	v_mul_f32_e32 v155, s83, v31
	v_mul_f32_e32 v156, s83, v32
	v_mul_f32_e32 v157, s83, v33
	v_mul_f32_e32 v158, s83, v26
	v_mul_f32_e32 v159, s83, v27
; DI v4u pack8(f32x4 a, f32x4 b) { v4u w; w.x = cvtpk(a[0], a[1]); w.y = cvtpk(a[2], a[3]); w.z = cvtpk(b[0], b[1]); w.w = cvtpk(b[2], b[3]); return w; }
; DI float fexp2(float x) { return __builtin_amdgcn_exp2f(x); }
; DI float silu_f(float z) { return z * __builtin_amdgcn_rcpf(1.f + fexp2(-z * LOG2E)); }
;     DI void operator()(const f32x4 (&acc)[2][2][4][2], const pg8::Unit& u, int wr, int wc, int fr, int fq) const {
;     ...
;                     if (kind == 2) {
; #pragma unroll
;                         for (int e = 0; e < 4; ++e) { v0[e] = silu_f(v0[e]); v1[e] = silu_f(v1[e]); } }
;                     else { v0 = v0 * sc; v1 = v1 * sc; }
;                     *(v4u*)(dst + (size_t)row * ld + col) = pack8(v0, v1); } }
	v_mul_f32_e32 v160, s83, v28
	v_mul_f32_e32 v161, s83, v29
	v_cvt_pk_bf16_f32 v130, v154, v155
	v_cvt_pk_bf16_f32 v131, v156, v157
	v_cvt_pk_bf16_f32 v132, v158, v159
	v_cvt_pk_bf16_f32 v133, v160, v161
	global_store_dwordx4 v153, v[130:133], s[4:5]
	v_mul_f32_e32 v154, s83, v22
	v_mul_f32_e32 v155, s83, v23
	v_mul_f32_e32 v156, s83, v24
	v_mul_f32_e32 v157, s83, v25
	v_mul_f32_e32 v158, s83, v18
	v_mul_f32_e32 v159, s83, v19
	v_mul_f32_e32 v160, s83, v20
	v_mul_f32_e32 v161, s83, v21
	v_cvt_pk_bf16_f32 v130, v154, v155
	v_cvt_pk_bf16_f32 v131, v156, v157
	v_cvt_pk_bf16_f32 v132, v158, v159
	v_cvt_pk_bf16_f32 v133, v160, v161
	global_store_dwordx4 v153, v[130:133], s[4:5] offset:256
	v_add_u32_e32 v153, s92, v153
	v_mul_f32_e32 v154, s83, v14
	v_mul_f32_e32 v155, s83, v15
	v_mul_f32_e32 v156, s83, v16
	v_mul_f32_e32 v157, s83, v17
	v_mul_f32_e32 v158, s83, v10
	v_mul_f32_e32 v159, s83, v11
	v_mul_f32_e32 v160, s83, v12
	v_mul_f32_e32 v161, s83, v13
	v_cvt_pk_bf16_f32 v130, v154, v155
	v_cvt_pk_bf16_f32 v131, v156, v157
	v_cvt_pk_bf16_f32 v132, v158, v159
	v_cvt_pk_bf16_f32 v133, v160, v161
	global_store_dwordx4 v153, v[130:133], s[4:5]
	v_mul_f32_e32 v154, s83, v6
	v_mul_f32_e32 v155, s83, v7
	v_mul_f32_e32 v156, s83, v8
	v_mul_f32_e32 v157, s83, v9
	v_mul_f32_e32 v158, s83, v2
	v_mul_f32_e32 v159, s83, v3
	v_mul_f32_e32 v160, s83, v4
	v_mul_f32_e32 v161, s83, v5
	v_cvt_pk_bf16_f32 v130, v154, v155
	v_cvt_pk_bf16_f32 v131, v156, v157
	v_cvt_pk_bf16_f32 v132, v158, v159
	v_cvt_pk_bf16_f32 v133, v160, v161
	global_store_dwordx4 v153, v[130:133], s[4:5] offset:256
	s_branch .LBB0_374
.Lep_silu:
	v_mul_f32_e32 v154, 0xbfb8aa3b, v126
	v_mul_f32_e32 v155, 0xbfb8aa3b, v127
	v_mul_f32_e32 v156, 0xbfb8aa3b, v128
	v_mul_f32_e32 v157, 0xbfb8aa3b, v129
	v_mul_f32_e32 v158, 0xbfb8aa3b, v122
	v_mul_f32_e32 v159, 0xbfb8aa3b, v123
	v_mul_f32_e32 v160, 0xbfb8aa3b, v124
	v_mul_f32_e32 v161, 0xbfb8aa3b, v125
	v_exp_f32_e32 v154, v154
	v_exp_f32_e32 v155, v155
	v_exp_f32_e32 v156, v156
	v_exp_f32_e32 v157, v157
	v_exp_f32_e32 v158, v158
	v_exp_f32_e32 v159, v159
	v_exp_f32_e32 v160, v160
	v_exp_f32_e32 v161, v161
	v_add_f32_e32 v154, 1.0, v154
	v_add_f32_e32 v155, 1.0, v155
	v_add_f32_e32 v156, 1.0, v156
	v_add_f32_e32 v157, 1.0, v157
	v_add_f32_e32 v158, 1.0, v158
	v_add_f32_e32 v159, 1.0, v159
	v_add_f32_e32 v160, 1.0, v160
	v_add_f32_e32 v161, 1.0, v161
	v_rcp_f32_e32 v154, v154
	v_rcp_f32_e32 v155, v155
	v_rcp_f32_e32 v156, v156
	v_rcp_f32_e32 v157, v157
	v_rcp_f32_e32 v158, v158
	v_rcp_f32_e32 v159, v159
	v_rcp_f32_e32 v160, v160
	v_rcp_f32_e32 v161, v161
	v_mul_f32_e32 v154, v126, v154
	v_mul_f32_e32 v155, v127, v155
	v_mul_f32_e32 v156, v128, v156
	v_mul_f32_e32 v157, v129, v157
	v_mul_f32_e32 v158, v122, v158
	v_mul_f32_e32 v159, v123, v159
	v_mul_f32_e32 v160, v124, v160
	v_mul_f32_e32 v161, v125, v161
	v_cvt_pk_bf16_f32 v130, v154, v155
	v_cvt_pk_bf16_f32 v131, v156, v157
	v_cvt_pk_bf16_f32 v132, v158, v159
	v_cvt_pk_bf16_f32 v133, v160, v161
	global_store_dwordx4 v153, v[130:133], s[4:5]
	v_mul_f32_e32 v154, 0xbfb8aa3b, v118
	v_mul_f32_e32 v155, 0xbfb8aa3b, v119
	v_mul_f32_e32 v156, 0xbfb8aa3b, v120
	v_mul_f32_e32 v157, 0xbfb8aa3b, v121
	v_mul_f32_e32 v158, 0xbfb8aa3b, v114
	v_mul_f32_e32 v159, 0xbfb8aa3b, v115
	v_mul_f32_e32 v160, 0xbfb8aa3b, v116
	v_mul_f32_e32 v161, 0xbfb8aa3b, v117
	v_exp_f32_e32 v154, v154
	v_exp_f32_e32 v155, v155
	v_exp_f32_e32 v156, v156
	v_exp_f32_e32 v157, v157
	v_exp_f32_e32 v158, v158
	v_exp_f32_e32 v159, v159
	v_exp_f32_e32 v160, v160
	v_exp_f32_e32 v161, v161
	v_add_f32_e32 v154, 1.0, v154
	v_add_f32_e32 v155, 1.0, v155
	v_add_f32_e32 v156, 1.0, v156
	v_add_f32_e32 v157, 1.0, v157
	v_add_f32_e32 v158, 1.0, v158
	v_add_f32_e32 v159, 1.0, v159
	v_add_f32_e32 v160, 1.0, v160
	v_add_f32_e32 v161, 1.0, v161
	v_rcp_f32_e32 v154, v154
	v_rcp_f32_e32 v155, v155
	v_rcp_f32_e32 v156, v156
	v_rcp_f32_e32 v157, v157
	v_rcp_f32_e32 v158, v158
	v_rcp_f32_e32 v159, v159
	v_rcp_f32_e32 v160, v160
	v_rcp_f32_e32 v161, v161
	v_mul_f32_e32 v154, v118, v154
	v_mul_f32_e32 v155, v119, v155
	v_mul_f32_e32 v156, v120, v156
	v_mul_f32_e32 v157, v121, v157
	v_mul_f32_e32 v158, v114, v158
	v_mul_f32_e32 v159, v115, v159
	v_mul_f32_e32 v160, v116, v160
	v_mul_f32_e32 v161, v117, v161
	v_cvt_pk_bf16_f32 v130, v154, v155
	v_cvt_pk_bf16_f32 v131, v156, v157
	v_cvt_pk_bf16_f32 v132, v158, v159
	v_cvt_pk_bf16_f32 v133, v160, v161
	global_store_dwordx4 v153, v[130:133], s[4:5] offset:256
	v_add_u32_e32 v153, s92, v153
	v_mul_f32_e32 v154, 0xbfb8aa3b, v110
	v_mul_f32_e32 v155, 0xbfb8aa3b, v111
	v_mul_f32_e32 v156, 0xbfb8aa3b, v112
	v_mul_f32_e32 v157, 0xbfb8aa3b, v113
	v_mul_f32_e32 v158, 0xbfb8aa3b, v106
	v_mul_f32_e32 v159, 0xbfb8aa3b, v107
	v_mul_f32_e32 v160, 0xbfb8aa3b, v108
	v_mul_f32_e32 v161, 0xbfb8aa3b, v109
	v_exp_f32_e32 v154, v154
	v_exp_f32_e32 v155, v155
	v_exp_f32_e32 v156, v156
	v_exp_f32_e32 v157, v157
	v_exp_f32_e32 v158, v158
	v_exp_f32_e32 v159, v159
	v_exp_f32_e32 v160, v160
	v_exp_f32_e32 v161, v161
	v_add_f32_e32 v154, 1.0, v154
	v_add_f32_e32 v155, 1.0, v155
	v_add_f32_e32 v156, 1.0, v156
	v_add_f32_e32 v157, 1.0, v157
	v_add_f32_e32 v158, 1.0, v158
	v_add_f32_e32 v159, 1.0, v159
	v_add_f32_e32 v160, 1.0, v160
	v_add_f32_e32 v161, 1.0, v161
	v_rcp_f32_e32 v154, v154
	v_rcp_f32_e32 v155, v155
	v_rcp_f32_e32 v156, v156
	v_rcp_f32_e32 v157, v157
	v_rcp_f32_e32 v158, v158
	v_rcp_f32_e32 v159, v159
	v_rcp_f32_e32 v160, v160
	v_rcp_f32_e32 v161, v161
	v_mul_f32_e32 v154, v110, v154
	v_mul_f32_e32 v155, v111, v155
	v_mul_f32_e32 v156, v112, v156
	v_mul_f32_e32 v157, v113, v157
	v_mul_f32_e32 v158, v106, v158
	v_mul_f32_e32 v159, v107, v159
; DI v4u pack8(f32x4 a, f32x4 b) { v4u w; w.x = cvtpk(a[0], a[1]); w.y = cvtpk(a[2], a[3]); w.z = cvtpk(b[0], b[1]); w.w = cvtpk(b[2], b[3]); return w; }
; DI float fexp2(float x) { return __builtin_amdgcn_exp2f(x); }
; DI float silu_f(float z) { return z * __builtin_amdgcn_rcpf(1.f + fexp2(-z * LOG2E)); }
;     DI void operator()(const f32x4 (&acc)[2][2][4][2], const pg8::Unit& u, int wr, int wc, int fr, int fq) const {
;     ...
;                     if (kind == 2) {
; #pragma unroll
;                         for (int e = 0; e < 4; ++e) { v0[e] = silu_f(v0[e]); v1[e] = silu_f(v1[e]); } }
;                     else { v0 = v0 * sc; v1 = v1 * sc; }
;                     *(v4u*)(dst + (size_t)row * ld + col) = pack8(v0, v1); } }
	v_mul_f32_e32 v160, v108, v160
	v_mul_f32_e32 v161, v109, v161
	v_cvt_pk_bf16_f32 v130, v154, v155
	v_cvt_pk_bf16_f32 v131, v156, v157
	v_cvt_pk_bf16_f32 v132, v158, v159
	v_cvt_pk_bf16_f32 v133, v160, v161
	global_store_dwordx4 v153, v[130:133], s[4:5]
	v_mul_f32_e32 v154, 0xbfb8aa3b, v102
	v_mul_f32_e32 v155, 0xbfb8aa3b, v103
	v_mul_f32_e32 v156, 0xbfb8aa3b, v104
	v_mul_f32_e32 v157, 0xbfb8aa3b, v105
	v_mul_f32_e32 v158, 0xbfb8aa3b, v98
	v_mul_f32_e32 v159, 0xbfb8aa3b, v99
	v_mul_f32_e32 v160, 0xbfb8aa3b, v100
	v_mul_f32_e32 v161, 0xbfb8aa3b, v101
	v_exp_f32_e32 v154, v154
	v_exp_f32_e32 v155, v155
	v_exp_f32_e32 v156, v156
	v_exp_f32_e32 v157, v157
	v_exp_f32_e32 v158, v158
	v_exp_f32_e32 v159, v159
	v_exp_f32_e32 v160, v160
	v_exp_f32_e32 v161, v161
	v_add_f32_e32 v154, 1.0, v154
	v_add_f32_e32 v155, 1.0, v155
	v_add_f32_e32 v156, 1.0, v156
	v_add_f32_e32 v157, 1.0, v157
	v_add_f32_e32 v158, 1.0, v158
	v_add_f32_e32 v159, 1.0, v159
	v_add_f32_e32 v160, 1.0, v160
	v_add_f32_e32 v161, 1.0, v161
	v_rcp_f32_e32 v154, v154
	v_rcp_f32_e32 v155, v155
	v_rcp_f32_e32 v156, v156
	v_rcp_f32_e32 v157, v157
	v_rcp_f32_e32 v158, v158
	v_rcp_f32_e32 v159, v159
	v_rcp_f32_e32 v160, v160
	v_rcp_f32_e32 v161, v161
	v_mul_f32_e32 v154, v102, v154
	v_mul_f32_e32 v155, v103, v155
	v_mul_f32_e32 v156, v104, v156
	v_mul_f32_e32 v157, v105, v157
	v_mul_f32_e32 v158, v98, v158
	v_mul_f32_e32 v159, v99, v159
	v_mul_f32_e32 v160, v100, v160
	v_mul_f32_e32 v161, v101, v161
	v_cvt_pk_bf16_f32 v130, v154, v155
	v_cvt_pk_bf16_f32 v131, v156, v157
	v_cvt_pk_bf16_f32 v132, v158, v159
	v_cvt_pk_bf16_f32 v133, v160, v161
	global_store_dwordx4 v153, v[130:133], s[4:5] offset:256
	v_add_u32_e32 v153, s92, v153
	v_mul_f32_e32 v154, 0xbfb8aa3b, v94
	v_mul_f32_e32 v155, 0xbfb8aa3b, v95
	v_mul_f32_e32 v156, 0xbfb8aa3b, v96
	v_mul_f32_e32 v157, 0xbfb8aa3b, v97
	v_mul_f32_e32 v158, 0xbfb8aa3b, v90
	v_mul_f32_e32 v159, 0xbfb8aa3b, v91
	v_mul_f32_e32 v160, 0xbfb8aa3b, v92
	v_mul_f32_e32 v161, 0xbfb8aa3b, v93
	v_exp_f32_e32 v154, v154
	v_exp_f32_e32 v155, v155
	v_exp_f32_e32 v156, v156
	v_exp_f32_e32 v157, v157
	v_exp_f32_e32 v158, v158
	v_exp_f32_e32 v159, v159
	v_exp_f32_e32 v160, v160
	v_exp_f32_e32 v161, v161
	v_add_f32_e32 v154, 1.0, v154
	v_add_f32_e32 v155, 1.0, v155
	v_add_f32_e32 v156, 1.0, v156
	v_add_f32_e32 v157, 1.0, v157
	v_add_f32_e32 v158, 1.0, v158
	v_add_f32_e32 v159, 1.0, v159
	v_add_f32_e32 v160, 1.0, v160
	v_add_f32_e32 v161, 1.0, v161
	v_rcp_f32_e32 v154, v154
	v_rcp_f32_e32 v155, v155
	v_rcp_f32_e32 v156, v156
	v_rcp_f32_e32 v157, v157
	v_rcp_f32_e32 v158, v158
	v_rcp_f32_e32 v159, v159
	v_rcp_f32_e32 v160, v160
	v_rcp_f32_e32 v161, v161
	v_mul_f32_e32 v154, v94, v154
	v_mul_f32_e32 v155, v95, v155
	v_mul_f32_e32 v156, v96, v156
	v_mul_f32_e32 v157, v97, v157
	v_mul_f32_e32 v158, v90, v158
	v_mul_f32_e32 v159, v91, v159
	v_mul_f32_e32 v160, v92, v160
	v_mul_f32_e32 v161, v93, v161
	v_cvt_pk_bf16_f32 v130, v154, v155
	v_cvt_pk_bf16_f32 v131, v156, v157
	v_cvt_pk_bf16_f32 v132, v158, v159
	v_cvt_pk_bf16_f32 v133, v160, v161
	global_store_dwordx4 v153, v[130:133], s[4:5]
	v_mul_f32_e32 v154, 0xbfb8aa3b, v86
	v_mul_f32_e32 v155, 0xbfb8aa3b, v87
	v_mul_f32_e32 v156, 0xbfb8aa3b, v88
	v_mul_f32_e32 v157, 0xbfb8aa3b, v89
	v_mul_f32_e32 v158, 0xbfb8aa3b, v82
	v_mul_f32_e32 v159, 0xbfb8aa3b, v83
	v_mul_f32_e32 v160, 0xbfb8aa3b, v84
	v_mul_f32_e32 v161, 0xbfb8aa3b, v85
	v_exp_f32_e32 v154, v154
	v_exp_f32_e32 v155, v155
	v_exp_f32_e32 v156, v156
	v_exp_f32_e32 v157, v157
	v_exp_f32_e32 v158, v158
	v_exp_f32_e32 v159, v159
	v_exp_f32_e32 v160, v160
	v_exp_f32_e32 v161, v161
	v_add_f32_e32 v154, 1.0, v154
	v_add_f32_e32 v155, 1.0, v155
	v_add_f32_e32 v156, 1.0, v156
	v_add_f32_e32 v157, 1.0, v157
	v_add_f32_e32 v158, 1.0, v158
	v_add_f32_e32 v159, 1.0, v159
	v_add_f32_e32 v160, 1.0, v160
	v_add_f32_e32 v161, 1.0, v161
	v_rcp_f32_e32 v154, v154
	v_rcp_f32_e32 v155, v155
	v_rcp_f32_e32 v156, v156
	v_rcp_f32_e32 v157, v157
	v_rcp_f32_e32 v158, v158
	v_rcp_f32_e32 v159, v159
	v_rcp_f32_e32 v160, v160
	v_rcp_f32_e32 v161, v161
	v_mul_f32_e32 v154, v86, v154
	v_mul_f32_e32 v155, v87, v155
	v_mul_f32_e32 v156, v88, v156
	v_mul_f32_e32 v157, v89, v157
	v_mul_f32_e32 v158, v82, v158
	v_mul_f32_e32 v159, v83, v159
	v_mul_f32_e32 v160, v84, v160
	v_mul_f32_e32 v161, v85, v161
	v_cvt_pk_bf16_f32 v130, v154, v155
	v_cvt_pk_bf16_f32 v131, v156, v157
	v_cvt_pk_bf16_f32 v132, v158, v159
	v_cvt_pk_bf16_f32 v133, v160, v161
	global_store_dwordx4 v153, v[130:133], s[4:5] offset:256
	v_add_u32_e32 v153, s92, v153
	v_mul_f32_e32 v154, 0xbfb8aa3b, v78
	v_mul_f32_e32 v155, 0xbfb8aa3b, v79
	v_mul_f32_e32 v156, 0xbfb8aa3b, v80
	v_mul_f32_e32 v157, 0xbfb8aa3b, v81
	v_mul_f32_e32 v158, 0xbfb8aa3b, v74
	v_mul_f32_e32 v159, 0xbfb8aa3b, v75
	v_mul_f32_e32 v160, 0xbfb8aa3b, v76
	v_mul_f32_e32 v161, 0xbfb8aa3b, v77
	v_exp_f32_e32 v154, v154
	v_exp_f32_e32 v155, v155
	v_exp_f32_e32 v156, v156
	v_exp_f32_e32 v157, v157
	v_exp_f32_e32 v158, v158
	v_exp_f32_e32 v159, v159
	v_exp_f32_e32 v160, v160
	v_exp_f32_e32 v161, v161
	v_add_f32_e32 v154, 1.0, v154
	v_add_f32_e32 v155, 1.0, v155
	v_add_f32_e32 v156, 1.0, v156
	v_add_f32_e32 v157, 1.0, v157
	v_add_f32_e32 v158, 1.0, v158
	v_add_f32_e32 v159, 1.0, v159
	v_add_f32_e32 v160, 1.0, v160
	v_add_f32_e32 v161, 1.0, v161
	v_rcp_f32_e32 v154, v154
	v_rcp_f32_e32 v155, v155
	v_rcp_f32_e32 v156, v156
	v_rcp_f32_e32 v157, v157
	v_rcp_f32_e32 v158, v158
	v_rcp_f32_e32 v159, v159
	v_rcp_f32_e32 v160, v160
	v_rcp_f32_e32 v161, v161
	v_mul_f32_e32 v154, v78, v154
	v_mul_f32_e32 v155, v79, v155
	v_mul_f32_e32 v156, v80, v156
	v_mul_f32_e32 v157, v81, v157
; DI v4u pack8(f32x4 a, f32x4 b) { v4u w; w.x = cvtpk(a[0], a[1]); w.y = cvtpk(a[2], a[3]); w.z = cvtpk(b[0], b[1]); w.w = cvtpk(b[2], b[3]); return w; }
; DI float fexp2(float x) { return __builtin_amdgcn_exp2f(x); }
; DI float silu_f(float z) { return z * __builtin_amdgcn_rcpf(1.f + fexp2(-z * LOG2E)); }
;     DI void operator()(const f32x4 (&acc)[2][2][4][2], const pg8::Unit& u, int wr, int wc, int fr, int fq) const {
;     ...
;                     if (kind == 2) {
; #pragma unroll
;                         for (int e = 0; e < 4; ++e) { v0[e] = silu_f(v0[e]); v1[e] = silu_f(v1[e]); } }
;                     else { v0 = v0 * sc; v1 = v1 * sc; }
;                     *(v4u*)(dst + (size_t)row * ld + col) = pack8(v0, v1); } }
	v_mul_f32_e32 v158, v74, v158
	v_mul_f32_e32 v159, v75, v159
	v_mul_f32_e32 v160, v76, v160
	v_mul_f32_e32 v161, v77, v161
	v_cvt_pk_bf16_f32 v130, v154, v155
	v_cvt_pk_bf16_f32 v131, v156, v157
	v_cvt_pk_bf16_f32 v132, v158, v159
	v_cvt_pk_bf16_f32 v133, v160, v161
	global_store_dwordx4 v153, v[130:133], s[4:5]
	v_mul_f32_e32 v154, 0xbfb8aa3b, v70
	v_mul_f32_e32 v155, 0xbfb8aa3b, v71
	v_mul_f32_e32 v156, 0xbfb8aa3b, v72
	v_mul_f32_e32 v157, 0xbfb8aa3b, v73
	v_mul_f32_e32 v158, 0xbfb8aa3b, v66
	v_mul_f32_e32 v159, 0xbfb8aa3b, v67
	v_mul_f32_e32 v160, 0xbfb8aa3b, v68
	v_mul_f32_e32 v161, 0xbfb8aa3b, v69
	v_exp_f32_e32 v154, v154
	v_exp_f32_e32 v155, v155
	v_exp_f32_e32 v156, v156
	v_exp_f32_e32 v157, v157
	v_exp_f32_e32 v158, v158
	v_exp_f32_e32 v159, v159
	v_exp_f32_e32 v160, v160
	v_exp_f32_e32 v161, v161
	v_add_f32_e32 v154, 1.0, v154
	v_add_f32_e32 v155, 1.0, v155
	v_add_f32_e32 v156, 1.0, v156
	v_add_f32_e32 v157, 1.0, v157
	v_add_f32_e32 v158, 1.0, v158
	v_add_f32_e32 v159, 1.0, v159
	v_add_f32_e32 v160, 1.0, v160
	v_add_f32_e32 v161, 1.0, v161
	v_rcp_f32_e32 v154, v154
	v_rcp_f32_e32 v155, v155
	v_rcp_f32_e32 v156, v156
	v_rcp_f32_e32 v157, v157
	v_rcp_f32_e32 v158, v158
	v_rcp_f32_e32 v159, v159
	v_rcp_f32_e32 v160, v160
	v_rcp_f32_e32 v161, v161
	v_mul_f32_e32 v154, v70, v154
	v_mul_f32_e32 v155, v71, v155
	v_mul_f32_e32 v156, v72, v156
	v_mul_f32_e32 v157, v73, v157
	v_mul_f32_e32 v158, v66, v158
	v_mul_f32_e32 v159, v67, v159
	v_mul_f32_e32 v160, v68, v160
	v_mul_f32_e32 v161, v69, v161
	v_cvt_pk_bf16_f32 v130, v154, v155
	v_cvt_pk_bf16_f32 v131, v156, v157
	v_cvt_pk_bf16_f32 v132, v158, v159
	v_cvt_pk_bf16_f32 v133, v160, v161
	global_store_dwordx4 v153, v[130:133], s[4:5] offset:256
	v_add_u32_e32 v153, s93, v152
	v_mul_f32_e32 v154, 0xbfb8aa3b, v62
	v_mul_f32_e32 v155, 0xbfb8aa3b, v63
	v_mul_f32_e32 v156, 0xbfb8aa3b, v64
	v_mul_f32_e32 v157, 0xbfb8aa3b, v65
	v_mul_f32_e32 v158, 0xbfb8aa3b, v58
	v_mul_f32_e32 v159, 0xbfb8aa3b, v59
	v_mul_f32_e32 v160, 0xbfb8aa3b, v60
	v_mul_f32_e32 v161, 0xbfb8aa3b, v61
	v_exp_f32_e32 v154, v154
	v_exp_f32_e32 v155, v155
	v_exp_f32_e32 v156, v156
	v_exp_f32_e32 v157, v157
	v_exp_f32_e32 v158, v158
	v_exp_f32_e32 v159, v159
	v_exp_f32_e32 v160, v160
	v_exp_f32_e32 v161, v161
	v_add_f32_e32 v154, 1.0, v154
	v_add_f32_e32 v155, 1.0, v155
	v_add_f32_e32 v156, 1.0, v156
	v_add_f32_e32 v157, 1.0, v157
	v_add_f32_e32 v158, 1.0, v158
	v_add_f32_e32 v159, 1.0, v159
	v_add_f32_e32 v160, 1.0, v160
	v_add_f32_e32 v161, 1.0, v161
	v_rcp_f32_e32 v154, v154
	v_rcp_f32_e32 v155, v155
	v_rcp_f32_e32 v156, v156
	v_rcp_f32_e32 v157, v157
	v_rcp_f32_e32 v158, v158
	v_rcp_f32_e32 v159, v159
	v_rcp_f32_e32 v160, v160
	v_rcp_f32_e32 v161, v161
	v_mul_f32_e32 v154, v62, v154
	v_mul_f32_e32 v155, v63, v155
	v_mul_f32_e32 v156, v64, v156
	v_mul_f32_e32 v157, v65, v157
	v_mul_f32_e32 v158, v58, v158
	v_mul_f32_e32 v159, v59, v159
	v_mul_f32_e32 v160, v60, v160
	v_mul_f32_e32 v161, v61, v161
	v_cvt_pk_bf16_f32 v130, v154, v155
	v_cvt_pk_bf16_f32 v131, v156, v157
	v_cvt_pk_bf16_f32 v132, v158, v159
	v_cvt_pk_bf16_f32 v133, v160, v161
	global_store_dwordx4 v153, v[130:133], s[4:5]
	v_mul_f32_e32 v154, 0xbfb8aa3b, v54
	v_mul_f32_e32 v155, 0xbfb8aa3b, v55
	v_mul_f32_e32 v156, 0xbfb8aa3b, v56
	v_mul_f32_e32 v157, 0xbfb8aa3b, v57
	v_mul_f32_e32 v158, 0xbfb8aa3b, v50
	v_mul_f32_e32 v159, 0xbfb8aa3b, v51
	v_mul_f32_e32 v160, 0xbfb8aa3b, v52
	v_mul_f32_e32 v161, 0xbfb8aa3b, v53
	v_exp_f32_e32 v154, v154
	v_exp_f32_e32 v155, v155
	v_exp_f32_e32 v156, v156
	v_exp_f32_e32 v157, v157
	v_exp_f32_e32 v158, v158
	v_exp_f32_e32 v159, v159
	v_exp_f32_e32 v160, v160
	v_exp_f32_e32 v161, v161
	v_add_f32_e32 v154, 1.0, v154
	v_add_f32_e32 v155, 1.0, v155
	v_add_f32_e32 v156, 1.0, v156
	v_add_f32_e32 v157, 1.0, v157
	v_add_f32_e32 v158, 1.0, v158
	v_add_f32_e32 v159, 1.0, v159
	v_add_f32_e32 v160, 1.0, v160
	v_add_f32_e32 v161, 1.0, v161
	v_rcp_f32_e32 v154, v154
	v_rcp_f32_e32 v155, v155
	v_rcp_f32_e32 v156, v156
	v_rcp_f32_e32 v157, v157
	v_rcp_f32_e32 v158, v158
	v_rcp_f32_e32 v159, v159
	v_rcp_f32_e32 v160, v160
	v_rcp_f32_e32 v161, v161
	v_mul_f32_e32 v154, v54, v154
	v_mul_f32_e32 v155, v55, v155
	v_mul_f32_e32 v156, v56, v156
	v_mul_f32_e32 v157, v57, v157
	v_mul_f32_e32 v158, v50, v158
	v_mul_f32_e32 v159, v51, v159
	v_mul_f32_e32 v160, v52, v160
	v_mul_f32_e32 v161, v53, v161
	v_cvt_pk_bf16_f32 v130, v154, v155
	v_cvt_pk_bf16_f32 v131, v156, v157
	v_cvt_pk_bf16_f32 v132, v158, v159
	v_cvt_pk_bf16_f32 v133, v160, v161
	global_store_dwordx4 v153, v[130:133], s[4:5] offset:256
	v_add_u32_e32 v153, s92, v153
	v_mul_f32_e32 v154, 0xbfb8aa3b, v46
	v_mul_f32_e32 v155, 0xbfb8aa3b, v47
	v_mul_f32_e32 v156, 0xbfb8aa3b, v48
	v_mul_f32_e32 v157, 0xbfb8aa3b, v49
	v_mul_f32_e32 v158, 0xbfb8aa3b, v42
	v_mul_f32_e32 v159, 0xbfb8aa3b, v43
	v_mul_f32_e32 v160, 0xbfb8aa3b, v44
	v_mul_f32_e32 v161, 0xbfb8aa3b, v45
	v_exp_f32_e32 v154, v154
	v_exp_f32_e32 v155, v155
	v_exp_f32_e32 v156, v156
	v_exp_f32_e32 v157, v157
	v_exp_f32_e32 v158, v158
	v_exp_f32_e32 v159, v159
	v_exp_f32_e32 v160, v160
	v_exp_f32_e32 v161, v161
	v_add_f32_e32 v154, 1.0, v154
	v_add_f32_e32 v155, 1.0, v155
	v_add_f32_e32 v156, 1.0, v156
	v_add_f32_e32 v157, 1.0, v157
	v_add_f32_e32 v158, 1.0, v158
	v_add_f32_e32 v159, 1.0, v159
	v_add_f32_e32 v160, 1.0, v160
	v_add_f32_e32 v161, 1.0, v161
	v_rcp_f32_e32 v154, v154
	v_rcp_f32_e32 v155, v155
	v_rcp_f32_e32 v156, v156
	v_rcp_f32_e32 v157, v157
	v_rcp_f32_e32 v158, v158
	v_rcp_f32_e32 v159, v159
	v_rcp_f32_e32 v160, v160
	v_rcp_f32_e32 v161, v161
	v_mul_f32_e32 v154, v46, v154
	v_mul_f32_e32 v155, v47, v155
	v_mul_f32_e32 v156, v48, v156
; DI v4u pack8(f32x4 a, f32x4 b) { v4u w; w.x = cvtpk(a[0], a[1]); w.y = cvtpk(a[2], a[3]); w.z = cvtpk(b[0], b[1]); w.w = cvtpk(b[2], b[3]); return w; }
; DI float fexp2(float x) { return __builtin_amdgcn_exp2f(x); }
; DI float silu_f(float z) { return z * __builtin_amdgcn_rcpf(1.f + fexp2(-z * LOG2E)); }
;     DI void operator()(const f32x4 (&acc)[2][2][4][2], const pg8::Unit& u, int wr, int wc, int fr, int fq) const {
;     ...
;                     if (kind == 2) {
; #pragma unroll
;                         for (int e = 0; e < 4; ++e) { v0[e] = silu_f(v0[e]); v1[e] = silu_f(v1[e]); } }
;                     else { v0 = v0 * sc; v1 = v1 * sc; }
;                     *(v4u*)(dst + (size_t)row * ld + col) = pack8(v0, v1); } }
	v_mul_f32_e32 v157, v49, v157
	v_mul_f32_e32 v158, v42, v158
	v_mul_f32_e32 v159, v43, v159
	v_mul_f32_e32 v160, v44, v160
	v_mul_f32_e32 v161, v45, v161
	v_cvt_pk_bf16_f32 v130, v154, v155
	v_cvt_pk_bf16_f32 v131, v156, v157
	v_cvt_pk_bf16_f32 v132, v158, v159
	v_cvt_pk_bf16_f32 v133, v160, v161
	global_store_dwordx4 v153, v[130:133], s[4:5]
	v_mul_f32_e32 v154, 0xbfb8aa3b, v38
	v_mul_f32_e32 v155, 0xbfb8aa3b, v39
	v_mul_f32_e32 v156, 0xbfb8aa3b, v40
	v_mul_f32_e32 v157, 0xbfb8aa3b, v41
	v_mul_f32_e32 v158, 0xbfb8aa3b, v34
	v_mul_f32_e32 v159, 0xbfb8aa3b, v35
	v_mul_f32_e32 v160, 0xbfb8aa3b, v36
	v_mul_f32_e32 v161, 0xbfb8aa3b, v37
	v_exp_f32_e32 v154, v154
	v_exp_f32_e32 v155, v155
	v_exp_f32_e32 v156, v156
	v_exp_f32_e32 v157, v157
	v_exp_f32_e32 v158, v158
	v_exp_f32_e32 v159, v159
	v_exp_f32_e32 v160, v160
	v_exp_f32_e32 v161, v161
	v_add_f32_e32 v154, 1.0, v154
	v_add_f32_e32 v155, 1.0, v155
	v_add_f32_e32 v156, 1.0, v156
	v_add_f32_e32 v157, 1.0, v157
	v_add_f32_e32 v158, 1.0, v158
	v_add_f32_e32 v159, 1.0, v159
	v_add_f32_e32 v160, 1.0, v160
	v_add_f32_e32 v161, 1.0, v161
	v_rcp_f32_e32 v154, v154
	v_rcp_f32_e32 v155, v155
	v_rcp_f32_e32 v156, v156
	v_rcp_f32_e32 v157, v157
	v_rcp_f32_e32 v158, v158
	v_rcp_f32_e32 v159, v159
	v_rcp_f32_e32 v160, v160
	v_rcp_f32_e32 v161, v161
	v_mul_f32_e32 v154, v38, v154
	v_mul_f32_e32 v155, v39, v155
	v_mul_f32_e32 v156, v40, v156
	v_mul_f32_e32 v157, v41, v157
	v_mul_f32_e32 v158, v34, v158
	v_mul_f32_e32 v159, v35, v159
	v_mul_f32_e32 v160, v36, v160
	v_mul_f32_e32 v161, v37, v161
	v_cvt_pk_bf16_f32 v130, v154, v155
	v_cvt_pk_bf16_f32 v131, v156, v157
	v_cvt_pk_bf16_f32 v132, v158, v159
	v_cvt_pk_bf16_f32 v133, v160, v161
	global_store_dwordx4 v153, v[130:133], s[4:5] offset:256
	v_add_u32_e32 v153, s92, v153
	v_mul_f32_e32 v154, 0xbfb8aa3b, v30
	v_mul_f32_e32 v155, 0xbfb8aa3b, v31
	v_mul_f32_e32 v156, 0xbfb8aa3b, v32
	v_mul_f32_e32 v157, 0xbfb8aa3b, v33
	v_mul_f32_e32 v158, 0xbfb8aa3b, v26
	v_mul_f32_e32 v159, 0xbfb8aa3b, v27
	v_mul_f32_e32 v160, 0xbfb8aa3b, v28
	v_mul_f32_e32 v161, 0xbfb8aa3b, v29
	v_exp_f32_e32 v154, v154
	v_exp_f32_e32 v155, v155
	v_exp_f32_e32 v156, v156
	v_exp_f32_e32 v157, v157
	v_exp_f32_e32 v158, v158
	v_exp_f32_e32 v159, v159
	v_exp_f32_e32 v160, v160
	v_exp_f32_e32 v161, v161
	v_add_f32_e32 v154, 1.0, v154
	v_add_f32_e32 v155, 1.0, v155
	v_add_f32_e32 v156, 1.0, v156
	v_add_f32_e32 v157, 1.0, v157
	v_add_f32_e32 v158, 1.0, v158
	v_add_f32_e32 v159, 1.0, v159
	v_add_f32_e32 v160, 1.0, v160
	v_add_f32_e32 v161, 1.0, v161
	v_rcp_f32_e32 v154, v154
	v_rcp_f32_e32 v155, v155
	v_rcp_f32_e32 v156, v156
	v_rcp_f32_e32 v157, v157
	v_rcp_f32_e32 v158, v158
	v_rcp_f32_e32 v159, v159
	v_rcp_f32_e32 v160, v160
	v_rcp_f32_e32 v161, v161
	v_mul_f32_e32 v154, v30, v154
	v_mul_f32_e32 v155, v31, v155
	v_mul_f32_e32 v156, v32, v156
	v_mul_f32_e32 v157, v33, v157
	v_mul_f32_e32 v158, v26, v158
	v_mul_f32_e32 v159, v27, v159
	v_mul_f32_e32 v160, v28, v160
	v_mul_f32_e32 v161, v29, v161
	v_cvt_pk_bf16_f32 v130, v154, v155
	v_cvt_pk_bf16_f32 v131, v156, v157
	v_cvt_pk_bf16_f32 v132, v158, v159
	v_cvt_pk_bf16_f32 v133, v160, v161
	global_store_dwordx4 v153, v[130:133], s[4:5]
	v_mul_f32_e32 v154, 0xbfb8aa3b, v22
	v_mul_f32_e32 v155, 0xbfb8aa3b, v23
	v_mul_f32_e32 v156, 0xbfb8aa3b, v24
	v_mul_f32_e32 v157, 0xbfb8aa3b, v25
	v_mul_f32_e32 v158, 0xbfb8aa3b, v18
	v_mul_f32_e32 v159, 0xbfb8aa3b, v19
	v_mul_f32_e32 v160, 0xbfb8aa3b, v20
	v_mul_f32_e32 v161, 0xbfb8aa3b, v21
	v_exp_f32_e32 v154, v154
	v_exp_f32_e32 v155, v155
	v_exp_f32_e32 v156, v156
	v_exp_f32_e32 v157, v157
	v_exp_f32_e32 v158, v158
	v_exp_f32_e32 v159, v159
	v_exp_f32_e32 v160, v160
	v_exp_f32_e32 v161, v161
	v_add_f32_e32 v154, 1.0, v154
; DI v4u pack8(f32x4 a, f32x4 b) { v4u w; w.x = cvtpk(a[0], a[1]); w.y = cvtpk(a[2], a[3]); w.z = cvtpk(b[0], b[1]); w.w = cvtpk(b[2], b[3]); return w; }
; DI float fexp2(float x) { return __builtin_amdgcn_exp2f(x); }
; DI float silu_f(float z) { return z * __builtin_amdgcn_rcpf(1.f + fexp2(-z * LOG2E)); }
;     DI void operator()(const f32x4 (&acc)[2][2][4][2], const pg8::Unit& u, int wr, int wc, int fr, int fq) const {
;     ...
;                     if (kind == 2) {
; #pragma unroll
;                         for (int e = 0; e < 4; ++e) { v0[e] = silu_f(v0[e]); v1[e] = silu_f(v1[e]); } }
;                     else { v0 = v0 * sc; v1 = v1 * sc; }
;                     *(v4u*)(dst + (size_t)row * ld + col) = pack8(v0, v1); } }
	v_add_f32_e32 v155, 1.0, v155
	v_add_f32_e32 v156, 1.0, v156
	v_add_f32_e32 v157, 1.0, v157
	v_add_f32_e32 v158, 1.0, v158
	v_add_f32_e32 v159, 1.0, v159
	v_add_f32_e32 v160, 1.0, v160
	v_add_f32_e32 v161, 1.0, v161
	v_rcp_f32_e32 v154, v154
	v_rcp_f32_e32 v155, v155
	v_rcp_f32_e32 v156, v156
	v_rcp_f32_e32 v157, v157
	v_rcp_f32_e32 v158, v158
	v_rcp_f32_e32 v159, v159
	v_rcp_f32_e32 v160, v160
	v_rcp_f32_e32 v161, v161
	v_mul_f32_e32 v154, v22, v154
	v_mul_f32_e32 v155, v23, v155
	v_mul_f32_e32 v156, v24, v156
	v_mul_f32_e32 v157, v25, v157
	v_mul_f32_e32 v158, v18, v158
	v_mul_f32_e32 v159, v19, v159
	v_mul_f32_e32 v160, v20, v160
	v_mul_f32_e32 v161, v21, v161
	v_cvt_pk_bf16_f32 v130, v154, v155
	v_cvt_pk_bf16_f32 v131, v156, v157
	v_cvt_pk_bf16_f32 v132, v158, v159
	v_cvt_pk_bf16_f32 v133, v160, v161
	global_store_dwordx4 v153, v[130:133], s[4:5] offset:256
	v_add_u32_e32 v153, s92, v153
	v_mul_f32_e32 v154, 0xbfb8aa3b, v14
	v_mul_f32_e32 v155, 0xbfb8aa3b, v15
	v_mul_f32_e32 v156, 0xbfb8aa3b, v16
	v_mul_f32_e32 v157, 0xbfb8aa3b, v17
	v_mul_f32_e32 v158, 0xbfb8aa3b, v10
	v_mul_f32_e32 v159, 0xbfb8aa3b, v11
	v_mul_f32_e32 v160, 0xbfb8aa3b, v12
	v_mul_f32_e32 v161, 0xbfb8aa3b, v13
	v_exp_f32_e32 v154, v154
	v_exp_f32_e32 v155, v155
	v_exp_f32_e32 v156, v156
	v_exp_f32_e32 v157, v157
	v_exp_f32_e32 v158, v158
	v_exp_f32_e32 v159, v159
	v_exp_f32_e32 v160, v160
	v_exp_f32_e32 v161, v161
	v_add_f32_e32 v154, 1.0, v154
	v_add_f32_e32 v155, 1.0, v155
	v_add_f32_e32 v156, 1.0, v156
	v_add_f32_e32 v157, 1.0, v157
	v_add_f32_e32 v158, 1.0, v158
	v_add_f32_e32 v159, 1.0, v159
	v_add_f32_e32 v160, 1.0, v160
	v_add_f32_e32 v161, 1.0, v161
	v_rcp_f32_e32 v154, v154
	v_rcp_f32_e32 v155, v155
	v_rcp_f32_e32 v156, v156
	v_rcp_f32_e32 v157, v157
	v_rcp_f32_e32 v158, v158
	v_rcp_f32_e32 v159, v159
	v_rcp_f32_e32 v160, v160
	v_rcp_f32_e32 v161, v161
	v_mul_f32_e32 v154, v14, v154
	v_mul_f32_e32 v155, v15, v155
	v_mul_f32_e32 v156, v16, v156
	v_mul_f32_e32 v157, v17, v157
	v_mul_f32_e32 v158, v10, v158
	v_mul_f32_e32 v159, v11, v159
	v_mul_f32_e32 v160, v12, v160
	v_mul_f32_e32 v161, v13, v161
	v_cvt_pk_bf16_f32 v130, v154, v155
	v_cvt_pk_bf16_f32 v131, v156, v157
	v_cvt_pk_bf16_f32 v132, v158, v159
	v_cvt_pk_bf16_f32 v133, v160, v161
	global_store_dwordx4 v153, v[130:133], s[4:5]
	v_mul_f32_e32 v154, 0xbfb8aa3b, v6
	v_mul_f32_e32 v155, 0xbfb8aa3b, v7
	v_mul_f32_e32 v156, 0xbfb8aa3b, v8
	v_mul_f32_e32 v157, 0xbfb8aa3b, v9
	v_mul_f32_e32 v158, 0xbfb8aa3b, v2
	v_mul_f32_e32 v159, 0xbfb8aa3b, v3
	v_mul_f32_e32 v160, 0xbfb8aa3b, v4
	v_mul_f32_e32 v161, 0xbfb8aa3b, v5
	v_exp_f32_e32 v154, v154
	v_exp_f32_e32 v155, v155
	v_exp_f32_e32 v156, v156
	v_exp_f32_e32 v157, v157
	v_exp_f32_e32 v158, v158
	v_exp_f32_e32 v159, v159
	v_exp_f32_e32 v160, v160
	v_exp_f32_e32 v161, v161
	v_add_f32_e32 v154, 1.0, v154
	v_add_f32_e32 v155, 1.0, v155
	v_add_f32_e32 v156, 1.0, v156
	v_add_f32_e32 v157, 1.0, v157
	v_add_f32_e32 v158, 1.0, v158
	v_add_f32_e32 v159, 1.0, v159
	v_add_f32_e32 v160, 1.0, v160
	v_add_f32_e32 v161, 1.0, v161
	v_rcp_f32_e32 v154, v154
	v_rcp_f32_e32 v155, v155
	v_rcp_f32_e32 v156, v156
	v_rcp_f32_e32 v157, v157
	v_rcp_f32_e32 v158, v158
	v_rcp_f32_e32 v159, v159
	v_rcp_f32_e32 v160, v160
	v_rcp_f32_e32 v161, v161
	v_mul_f32_e32 v154, v6, v154
	v_mul_f32_e32 v155, v7, v155
	v_mul_f32_e32 v156, v8, v156
	v_mul_f32_e32 v157, v9, v157
	v_mul_f32_e32 v158, v2, v158
	v_mul_f32_e32 v159, v3, v159
	v_mul_f32_e32 v160, v4, v160
	v_mul_f32_e32 v161, v5, v161
	v_cvt_pk_bf16_f32 v130, v154, v155
	v_cvt_pk_bf16_f32 v131, v156, v157
	v_cvt_pk_bf16_f32 v132, v158, v159
	v_cvt_pk_bf16_f32 v133, v160, v161
	global_store_dwordx4 v153, v[130:133], s[4:5] offset:256
	s_branch .LBB0_374

; #define LAS __attribute__((address_space(3)))
; DI int crow(int r, int hi) { return (r & 3) + 8 * (r >> 2) + 4 * hi; }
; template <class EpiT> ...
;     const int rt = c >> 4, cp = c & 15, tsel = wave & 1, ksub = wave >> 1, r32 = lane & 31, hh = lane >> 5;
;     LAS unsigned char* As = lds;
;     LAS unsigned char* Bs = lds + 32768;
;     f32x16 acc;
; #pragma unroll
;     for (int i = 0; i < 16; ++i) acc[i] = 0.f;
;     float xv[16];
; #pragma unroll
;     for (int i = 0; i < 16; ++i) xv[i] = (wave < 2) ? xs[(size_t)(32 * rt + crow(i, hh)) * D + 64 * cp + 32 * wave + r32] : 0.f;
;     v4u st[12];
; #pragma unroll
;     for (int i = 0; i < 12; ++i) { const int r = wave + 8 * i;
;         const bf16* src = (r < 32) ? MIX + (size_t)(MP + 32 * rt + r) * D : WT + (size_t)(64 * cp + (r - 32)) * D;
;         st[i] = *(const v4u*)(src + lane * 8); }
; #pragma unroll
;     for (int half = 0; half < 2; ++half) {
;         __syncthreads();
; #pragma unroll
;         for (int i = 0; i < 12; ++i) { const int r = wave + 8 * i; *(LAS v4u*)(lds + r * 1024 + ((lane ^ (r & 15)) << 4)) = st[i]; }
;         if (half == 0) {
; #pragma unroll
;             for (int i = 0; i < 12; ++i) { const int r = wave + 8 * i;
;                 const bf16* src = (r < 32) ? MIX + (size_t)(MP + 32 * rt + r) * D : WT + (size_t)(64 * cp + (r - 32)) * D;
;                 st[i] = *(const v4u*)(src + 512 + lane * 8); } }
;         __syncthreads();
.LBB0_940:
	s_add_u32 s8, s82, 0x10400000
	s_addc_u32 s9, s83, 0
	s_add_u32 s31, s82, 0x10700000
	s_addc_u32 s40, s83, 0
	s_add_i32 s14, s4, 0x4000
	s_sub_i32 s44, s13, 32
	s_add_i32 s4, s33, s14
	s_add_i32 s0, s33, s44
	s_ashr_i32 s1, s4, 31
	s_cmpk_lt_u32 s84, 0x800
	v_readlane_b32 s52, v247, 21
	s_cselect_b32 s1, s1, 0
	s_cselect_b32 s0, s4, s0
	v_readlane_b32 s53, v247, 22
	s_cselect_b32 s4, s37, s53
	s_cselect_b32 s5, s36, s52
	s_lshl_b64 s[0:1], s[0:1], 11
	s_add_u32 s0, s5, s0
	s_addc_u32 s1, s4, s1
	s_add_i32 s45, s33, 8
	s_add_i32 s4, s45, s14
	s_ashr_i32 s5, s4, 31
	s_add_i32 s6, s45, s44
	s_cmpk_lt_u32 s84, 0x600
	s_cselect_b32 s5, s5, 0
	s_cselect_b32 s4, s4, s6
	s_cselect_b32 s6, s37, s53
	s_cselect_b32 s7, s36, s52
	s_lshl_b64 s[4:5], s[4:5], 11
	s_add_u32 s4, s7, s4
	s_addc_u32 s5, s6, s5
	s_add_i32 s46, s33, 16
	s_add_i32 s6, s46, s14
	s_ashr_i32 s7, s6, 31
	s_add_i32 s15, s46, s44
	s_cmpk_lt_u32 s84, 0x400
	s_cselect_b32 s7, s7, 0
	s_cselect_b32 s6, s6, s15
	s_cselect_b32 s15, s37, s53
	s_cselect_b32 s16, s36, s52
	s_lshl_b64 s[6:7], s[6:7], 11
	s_add_u32 s6, s16, s6
	s_addc_u32 s7, s15, s7
	s_add_i32 s47, s33, 24
	s_add_i32 s14, s47, s14
	s_ashr_i32 s15, s14, 31
	s_add_i32 s16, s47, s44
	s_cmpk_lt_u32 s84, 0x200
	s_cselect_b32 s15, s15, 0
	s_cselect_b32 s14, s14, s16
	s_cselect_b32 s16, s37, s53
	s_cselect_b32 s17, s36, s52
	s_lshl_b64 s[14:15], s[14:15], 11
	s_add_u32 s14, s17, s14
	s_mov_b32 s35, 0
	s_addc_u32 s15, s16, s15
	s_add_i32 s34, s33, s13
	s_lshl_b64 s[16:17], s[34:35], 11
	s_add_u32 s16, s52, s16
	s_addc_u32 s17, s53, s17
	s_add_i32 s48, s33, 40
	s_add_i32 s34, s48, s44
	s_lshl_b64 s[18:19], s[34:35], 11
	s_add_u32 s18, s52, s18
	s_addc_u32 s19, s53, s19
	s_add_i32 s49, s33, 48
	s_add_i32 s34, s49, s44
	s_lshl_b64 s[20:21], s[34:35], 11
	s_add_u32 s20, s52, s20
	s_addc_u32 s21, s53, s21
	s_add_i32 s50, s33, 56
	s_add_i32 s34, s50, s44
	s_lshl_b64 s[22:23], s[34:35], 11
	s_add_u32 s22, s52, s22
	s_addc_u32 s23, s53, s23
	s_add_i32 s51, s33, 64
	s_add_i32 s34, s51, s44
	s_lshl_b64 s[26:27], s[34:35], 11
	s_add_u32 s26, s52, s26
	s_addc_u32 s27, s53, s27
	s_add_i32 s56, s33, 0x48
	s_add_i32 s34, s56, s44
	s_lshl_b64 s[28:29], s[34:35], 11
	s_add_u32 s28, s52, s28
	s_addc_u32 s29, s53, s29
	s_add_i32 s57, s33, 0x50
	s_add_i32 s34, s57, s44
	s_lshl_b64 s[38:39], s[34:35], 11
	s_add_u32 s38, s52, s38
	s_addc_u32 s39, s53, s39
	s_add_i32 s58, s33, 0x58
	s_add_i32 s34, s58, s44
	s_lshl_b64 s[34:35], s[34:35], 11
	s_add_u32 s34, s52, s34
	v_lshlrev_b32_e32 v5, 4, v182
	s_addc_u32 s35, s53, s35
	global_load_dwordx4 v[6:9], v5, s[0:1]
	global_load_dwordx4 v[10:13], v5, s[4:5]
	global_load_dwordx4 v[14:17], v5, s[6:7]
	global_load_dwordx4 v[82:85], v5, s[14:15]
	global_load_dwordx4 v[86:89], v5, s[16:17]
	global_load_dwordx4 v[90:93], v5, s[18:19]
	global_load_dwordx4 v[94:97], v5, s[20:21]
	global_load_dwordx4 v[98:101], v5, s[22:23]
	global_load_dwordx4 v[102:105], v5, s[26:27]
	global_load_dwordx4 v[106:109], v5, s[28:29]
	global_load_dwordx4 v[110:113], v5, s[38:39]
	global_load_dwordx4 v[114:117], v5, s[34:35]
	v_and_or_b32 v2, s12, 32, v181
	s_lshl_b32 s60, s33, 4
	v_lshl_add_u32 v190, v2, 10, 0
	s_and_b32 s60, s60, 0x3fffffc0
	v_or_b32_e32 v2, s41, v1
	v_add_u32_e32 v191, s60, v2
	s_movk_i32 s44, 0x4000
	v_add_u32_e32 v2, 0x80, v191
	s_lshl_b32 s59, s33, 3
	v_add_u32_e32 v118, 0xffffc080, v191
	v_ashrrev_i32_e32 v3, 31, v2
	v_cmp_gt_i32_e32 vcc, s44, v2
	s_and_b32 s59, s59, 0xffffff0
	v_or_b32_e32 v183, s59, v4
	v_cndmask_b32_e32 v3, 0, v3, vcc
	v_cndmask_b32_e32 v2, v118, v2, vcc
	v_lshlrev_b64 v[142:143], 12, v[2:3]
	v_bitop3_b32 v2, s59, v1, v4 bitop3:0x36
	s_lshl_b32 s59, s33, 10
	v_bitop3_b32 v3, s33, v182, 15 bitop3:0x6c
	s_add_i32 s59, s59, 0
	v_lshlrev_b32_e32 v3, 4, v3
	v_add_u32_e32 v193, s59, v3
	s_lshl_b32 s59, s45, 10
	v_bitop3_b32 v4, s45, v182, 15 bitop3:0x6c
	s_lshl_b32 s45, s46, 10
	s_add_i32 s45, s45, 0
	s_add_i32 s59, s59, 0
	v_add_u32_e32 v195, s45, v3
	s_lshl_b32 s45, s47, 10
	v_lshl_add_u32 v194, v4, 4, s59
	s_add_i32 s45, s45, 0
	v_bitop3_b32 v4, s47, v182, 15 bitop3:0x6c
	v_lshl_add_u32 v196, v4, 4, s45
	s_lshl_b32 s45, s48, 10
	s_add_i32 s45, s45, 0
	v_bitop3_b32 v4, s48, v182, 15 bitop3:0x6c
	v_lshl_add_u32 v197, v4, 4, s45
	s_lshl_b32 s45, s49, 10
	s_add_i32 s45, s45, 0
	v_add_u32_e32 v198, s45, v3
	s_lshl_b32 s45, s50, 10
	s_add_i32 s45, s45, 0
	v_bitop3_b32 v4, s50, v182, 15 bitop3:0x6c
	v_lshl_add_u32 v199, v4, 4, s45
	s_lshl_b32 s45, s51, 10
	s_add_i32 s45, s45, 0
	v_add_u32_e32 v200, s45, v3
	s_lshl_b32 s45, s56, 10
	s_add_i32 s45, s45, 0
	v_bitop3_b32 v4, s56, v182, 15 bitop3:0x6c
	v_lshl_add_u32 v201, v4, 4, s45
	s_lshl_b32 s45, s57, 10
	s_add_i32 s45, s45, 0
	v_add_u32_e32 v202, s45, v3
	s_lshl_b32 s45, s58, 10
	s_add_i32 s45, s45, 0
	v_bitop3_b32 v3, s58, v182, 15 bitop3:0x6c
	v_lshl_add_u32 v203, v3, 4, s45
	s_waitcnt vmcnt(0)
	s_barrier
	v_lshlrev_b32_e32 v2, 4, v2
	v_lshl_add_u32 v185, v181, 10, 0
	v_add_u32_e32 v134, 0x90, v191
	v_add_u32_e32 v204, v190, v2
	v_add_u32_e32 v192, v185, v2
	v_add_u32_e32 v135, 0xffffc090, v191
	v_add_u32_e32 v144, 0xa0, v191
	v_add_u32_e32 v188, 0xffffc0a0, v191
	v_mov_b32_e32 v179, 0
	ds_write_b128 v193, v[6:9]
	ds_write_b128 v194, v[10:13]
	ds_write_b128 v195, v[14:17]
	ds_write_b128 v196, v[82:85]
	ds_write_b128 v193, v[86:89] offset:32768
	ds_write_b128 v197, v[90:93]
	ds_write_b128 v198, v[94:97]
	ds_write_b128 v199, v[98:101]
	ds_write_b128 v200, v[102:105]
	ds_write_b128 v201, v[106:109]
	ds_write_b128 v202, v[110:113]
	ds_write_b128 v203, v[114:117]
	global_load_dwordx4 v[82:85], v5, s[0:1] offset:1024
	global_load_dwordx4 v[86:89], v5, s[4:5] offset:1024
	global_load_dwordx4 v[90:93], v5, s[6:7] offset:1024
	global_load_dwordx4 v[94:97], v5, s[14:15] offset:1024
	global_load_dwordx4 v[98:101], v5, s[16:17] offset:1024
	global_load_dwordx4 v[102:105], v5, s[18:19] offset:1024
	global_load_dwordx4 v[106:109], v5, s[20:21] offset:1024
	global_load_dwordx4 v[110:113], v5, s[22:23] offset:1024
	global_load_dwordx4 v[114:117], v5, s[26:27] offset:1024
	global_load_dwordx4 v[118:121], v5, s[28:29] offset:1024
	global_load_dwordx4 v[122:125], v5, s[38:39] offset:1024
	global_load_dwordx4 v[126:129], v5, s[34:35] offset:1024
	s_waitcnt lgkmcnt(0)
	s_barrier
; #define LAS __attribute__((address_space(3)))
; #define MFMA32(a, b, c) __builtin_amdgcn_mfma_f32_32x32x16_bf16((a), (b), (c), 0, 0, 0)
;     DI void init_half(f32x4 (&acc)[2][4][2], int ai, const pg8::Unit& u, int wr, int wc, int fr, int fq) const {
;         const int rb = u.pm * 256 + wr * 64 + fr, cbase = u.pn * 256 + wc * 32 + 8 * fq;
; #pragma unroll
;         for (int m = 0; m < 4; ++m) { const int row = rb + ai * 128 + m * 16;
;             const float* xr = (row < MP) ? xp + (size_t)row * D : xs + (size_t)(row - MP) * D;
; #pragma unroll
;             for (int bj = 0; bj < 2; ++bj) { acc[bj][m][0] = *(const f32x4*)(xr + cbase + bj * 128); acc[bj][m][1] = *(const f32x4*)(xr + cbase + bj * 128 + 4); } }
;     }
; template <class EpiT> ...
;     ...
;     for (int half = 0; half < 2; ++half) {
;         __syncthreads();
; #pragma unroll
;         for (int i = 0; i < 12; ++i) { const int r = wave + 8 * i; *(LAS v4u*)(lds + r * 1024 + ((lane ^ (r & 15)) << 4)) = st[i]; }
;         if (half == 0) {
; #pragma unroll
;             for (int i = 0; i < 12; ++i) { const int r = wave + 8 * i;
;                 const bf16* src = (r < 32) ? MIX + (size_t)(MP + 32 * rt + r) * D : WT + (size_t)(64 * cp + (r - 32)) * D;
;                 st[i] = *(const v4u*)(src + 512 + lane * 8); } }
;         __syncthreads();
;         if (half == 1) E.init_half(acc1, 1, u0, wave >> 2, wave & 3, lane & 15, lane >> 4);
; #pragma unroll
;         for (int s8 = 0; s8 < 8; ++s8) { const int ch = 16 * ksub + 2 * s8 + hh;
;             const bf16x8 a = *(LAS const bf16x8*)(As + r32 * 1024 + ((ch ^ (r32 & 15)) << 4));
;             const bf16x8 bb = *(LAS const bf16x8*)(Bs + (32 * tsel + r32) * 1024 + ((ch ^ (r32 & 15)) << 4));
;             acc = MFMA32(a, bb, acc); }
	ds_read_b128 v[2:5], v204 offset:32768
	ds_read_b128 v[6:9], v192
	v_ashrrev_i32_e32 v10, 31, v134
	v_cmp_gt_i32_e64 s[4:5], s44, v134
	v_cmp_gt_i32_e64 s[6:7], s44, v144
	s_nop 0
	v_cndmask_b32_e64 v139, 0, v10, s[4:5]
	v_bitop3_b32 v10, v183, v1, 2 bitop3:0x36
	v_lshlrev_b32_e32 v136, 4, v10
	v_add_u32_e32 v205, v185, v136
	ds_read_b128 v[130:133], v205
	s_waitcnt lgkmcnt(1)
	v_mfma_f32_32x32x16_bf16 v[2:17], v[6:9], v[2:5], 0
	v_add_u32_e32 v206, v190, v136
	v_cndmask_b32_e64 v138, v135, v134, s[4:5]
	ds_read_b128 v[134:137], v206 offset:32768
	v_lshlrev_b64 v[186:187], 12, v[138:139]
	v_ashrrev_i32_e32 v138, 31, v144
	v_cndmask_b32_e64 v145, 0, v138, s[6:7]
	v_bitop3_b32 v138, v183, v1, 6 bitop3:0x36
	s_waitcnt lgkmcnt(0)
	v_mfma_f32_32x32x16_bf16 v[2:17], v[130:133], v[134:137], v[2:17]
	v_bitop3_b32 v130, v183, v1, 4 bitop3:0x36
	v_lshlrev_b32_e32 v134, 4, v130
	v_add_u32_e32 v207, v185, v134
	ds_read_b128 v[130:133], v207
	v_add_u32_e32 v208, v190, v134
	ds_read_b128 v[134:137], v208 offset:32768
	v_lshlrev_b32_e32 v189, 4, v138
	v_add_u32_e32 v209, v185, v189
	ds_read_b128 v[138:141], v209
	s_waitcnt lgkmcnt(1)
	v_mfma_f32_32x32x16_bf16 v[2:17], v[130:133], v[134:137], v[2:17]
	v_add_u32_e32 v210, v190, v189
	ds_read_b128 v[130:133], v210 offset:32768
	v_bitop3_b32 v134, v183, v1, 8 bitop3:0x36
	v_lshlrev_b32_e32 v211, 4, v134
	v_add_u32_e32 v212, v185, v211
	ds_read_b128 v[134:137], v212
	v_add_u32_e32 v211, v190, v211
	s_waitcnt lgkmcnt(1)
	v_mfma_f32_32x32x16_bf16 v[2:17], v[138:141], v[130:133], v[2:17]
	ds_read_b128 v[130:133], v211 offset:32768
	v_cndmask_b32_e64 v144, v188, v144, s[6:7]
	v_bitop3_b32 v138, v183, v1, 10 bitop3:0x36
	v_lshlrev_b64 v[188:189], 12, v[144:145]
	v_lshlrev_b32_e32 v144, 4, v138
	v_add_u32_e32 v213, v185, v144
	ds_read_b128 v[138:141], v213
	s_waitcnt lgkmcnt(1)
	v_mfma_f32_32x32x16_bf16 v[2:17], v[134:137], v[130:133], v[2:17]
	v_add_u32_e32 v214, v190, v144
	ds_read_b128 v[130:133], v214 offset:32768
	v_bitop3_b32 v134, v183, v1, 12 bitop3:0x36
	v_lshlrev_b32_e32 v144, 4, v134
	v_add_u32_e32 v215, v185, v144
	ds_read_b128 v[134:137], v215
	v_add_u32_e32 v217, v190, v144
	s_waitcnt lgkmcnt(1)
	v_mfma_f32_32x32x16_bf16 v[2:17], v[138:141], v[130:133], v[2:17]
	ds_read_b128 v[130:133], v217 offset:32768
	v_bitop3_b32 v138, v183, v1, 14 bitop3:0x36
	v_lshlrev_b32_e32 v144, 4, v138
	v_add_u32_e32 v183, v185, v144
	v_add_u32_e32 v145, 0xb0, v191
	ds_read_b128 v[138:141], v183
	v_cmp_gt_i32_e64 s[0:1], s44, v145
	s_waitcnt lgkmcnt(1)
	v_mfma_f32_32x32x16_bf16 v[2:17], v[134:137], v[130:133], v[2:17]
	v_readlane_b32 s44, v247, 2
	v_readlane_b32 s45, v247, 3
	v_add_u32_e32 v185, v190, v144
	v_readlane_b32 s46, v247, 4
	v_readlane_b32 s47, v247, 5
	s_mov_b64 s[16:17], s[44:45]
	ds_read_b128 v[130:133], v185 offset:32768
	s_mov_b64 s[18:19], s[46:47]
	s_waitcnt lgkmcnt(0)
	s_barrier
	s_waitcnt vmcnt(11)
	ds_write_b128 v193, v[82:85]
	s_waitcnt vmcnt(10)
	ds_write_b128 v194, v[86:89]
	s_waitcnt vmcnt(9)
	ds_write_b128 v195, v[90:93]
	s_waitcnt vmcnt(8)
	ds_write_b128 v196, v[94:97]
	s_waitcnt vmcnt(7)
	ds_write_b128 v193, v[98:101] offset:32768
	s_waitcnt vmcnt(6)
	ds_write_b128 v197, v[102:105]
	s_waitcnt vmcnt(5)
	ds_write_b128 v198, v[106:109]
	s_waitcnt vmcnt(4)
	ds_write_b128 v199, v[110:113]
	s_waitcnt vmcnt(3)
	ds_write_b128 v200, v[114:117]
	s_waitcnt vmcnt(2)
	ds_write_b128 v201, v[118:121]
	s_waitcnt vmcnt(1)
	ds_write_b128 v202, v[122:125]
	s_waitcnt vmcnt(0)
	ds_write_b128 v203, v[126:129]
	v_mov_b32_e32 v92, s19
	v_mov_b32_e32 v93, s17
	v_mov_b32_e32 v94, s18
	v_mov_b32_e32 v95, s16
	v_cndmask_b32_e32 v83, v92, v93, vcc
	v_cndmask_b32_e32 v82, v94, v95, vcc
	v_ashrrev_i32_e32 v216, 31, v145
	v_add_u32_e32 v134, 0xffffc0b0, v191
	v_lshl_add_u64 v[82:83], v[82:83], 0, v[142:143]
	v_cndmask_b32_e64 v135, 0, v216, s[0:1]
	v_cndmask_b32_e64 v134, v134, v145, s[0:1]
	v_lshl_add_u64 v[82:83], v[82:83], 0, v[178:179]
	v_lshlrev_b64 v[190:191], 12, v[134:135]
	v_mfma_f32_32x32x16_bf16 v[2:17], v[138:141], v[130:133], v[2:17]
	s_waitcnt lgkmcnt(0)
	s_barrier
	global_load_dwordx4 v[138:141], v[82:83], off offset:16
	global_load_dwordx4 v[142:145], v[82:83], off
	global_load_dwordx4 v[130:133], v[82:83], off offset:528
	global_load_dwordx4 v[134:137], v[82:83], off offset:512
	v_cndmask_b32_e64 v83, v92, v93, s[4:5]
	v_cndmask_b32_e64 v82, v94, v95, s[4:5]
	v_lshl_add_u64 v[82:83], v[82:83], 0, v[186:187]
	v_lshl_add_u64 v[82:83], v[82:83], 0, v[178:179]
	global_load_dwordx4 v[122:125], v[82:83], off offset:16
	global_load_dwordx4 v[126:129], v[82:83], off
	global_load_dwordx4 v[114:117], v[82:83], off offset:528
	global_load_dwordx4 v[118:121], v[82:83], off offset:512
	v_cndmask_b32_e64 v83, v92, v93, s[6:7]
	v_cndmask_b32_e64 v82, v94, v95, s[6:7]
	v_lshl_add_u64 v[82:83], v[82:83], 0, v[188:189]
	v_lshl_add_u64 v[90:91], v[82:83], 0, v[178:179]
	ds_read_b128 v[82:85], v192
	global_load_dwordx4 v[106:109], v[90:91], off offset:16
	global_load_dwordx4 v[110:113], v[90:91], off
	ds_read_b128 v[86:89], v204 offset:32768
	global_load_dwordx4 v[98:101], v[90:91], off offset:528
	global_load_dwordx4 v[102:105], v[90:91], off offset:512
	v_cndmask_b32_e64 v91, v92, v93, s[0:1]
	v_cndmask_b32_e64 v90, v94, v95, s[0:1]
	s_waitcnt lgkmcnt(0)
	v_mfma_f32_32x32x16_bf16 v[2:17], v[82:85], v[86:89], v[2:17]
	v_lshl_add_u64 v[82:83], v[90:91], 0, v[190:191]
	v_lshl_add_u64 v[86:87], v[82:83], 0, v[178:179]
	ds_read_b128 v[186:189], v205
	ds_read_b128 v[190:193], v206 offset:32768
	global_load_dwordx4 v[90:93], v[86:87], off offset:16
	global_load_dwordx4 v[94:97], v[86:87], off
	global_load_dwordx4 v[82:85], v[86:87], off offset:528
	s_nop 0
	global_load_dwordx4 v[86:89], v[86:87], off offset:512
	s_lshl_b32 s0, s33, 12
	s_add_i32 s1, s0, 0
	s_waitcnt lgkmcnt(0)
; #define LAS __attribute__((address_space(3)))
; DI int crow(int r, int hi) { return (r & 3) + 8 * (r >> 2) + 4 * hi; }
; template <class EpiT> ...
;     ...
;     __syncthreads();
;     LAS float* part = (LAS float*)lds;
; #pragma unroll
;     for (int i = 0; i < 16; ++i) part[(wave * 16 + i) * 64 + lane] = acc[i];
;     __syncthreads();
;     if (wave < 2) {
; #pragma unroll
;         for (int i = 0; i < 16; ++i) {
;             const float v0 = (part[(wave * 16 + i) * 64 + lane] + part[((wave + 2) * 16 + i) * 64 + lane]) + (part[((wave + 4) * 16 + i) * 64 + lane] + part[((wave + 6) * 16 + i) * 64 + lane]);
;             const int row = 32 * rt + crow(i, hh), col = 64 * cp + 32 * wave + r32, ct = 2 * cp + wave;
;             const float v = v0 + xv[i];
;             __hip_atomic_store((unsigned*)(XS2 + (size_t)row * D + col), __float_as_uint(v), __ATOMIC_RELAXED, __HIP_MEMORY_SCOPE_AGENT);
;             float q = v * v; q += __shfl_xor(q, 1); q += __shfl_xor(q, 2); q += __shfl_xor(q, 4); q += __shfl_xor(q, 8); q += __shfl_xor(q, 16);
;             if (r32 == 0) __hip_atomic_store((unsigned*)(SSQ + (size_t)row * 32 + ct), __float_as_uint(q), __ATOMIC_RELAXED, __HIP_MEMORY_SCOPE_AGENT);
;         }
;     }
	v_mfma_f32_32x32x16_bf16 v[2:17], v[186:189], v[190:193], v[2:17]
	ds_read_b128 v[186:189], v207
	ds_read_b128 v[190:193], v208 offset:32768
	v_readlane_b32 s6, v247, 23
	s_and_b64 vcc, exec, s[2:3]
	v_readlane_b32 s7, v247, 24
	v_readlane_b32 s48, v247, 6
	v_readlane_b32 s49, v247, 7
	v_readlane_b32 s50, v247, 8
	s_waitcnt lgkmcnt(0)
	v_mfma_f32_32x32x16_bf16 v[2:17], v[186:189], v[190:193], v[2:17]
	ds_read_b128 v[186:189], v209
	ds_read_b128 v[190:193], v210 offset:32768
	v_readlane_b32 s51, v247, 9
	v_readlane_b32 s52, v247, 10
	v_readlane_b32 s53, v247, 11
	v_readlane_b32 s54, v247, 12
	v_readlane_b32 s55, v247, 13
	v_readlane_b32 s56, v247, 14
	s_waitcnt lgkmcnt(0)
	v_mfma_f32_32x32x16_bf16 v[2:17], v[186:189], v[190:193], v[2:17]
	ds_read_b128 v[186:189], v212
	ds_read_b128 v[190:193], v211 offset:32768
	v_readlane_b32 s57, v247, 15
	v_readlane_b32 s58, v247, 16
	v_readlane_b32 s59, v247, 17
	s_waitcnt lgkmcnt(0)
	v_mfma_f32_32x32x16_bf16 v[2:17], v[186:189], v[190:193], v[2:17]
	ds_read_b128 v[186:189], v213
	ds_read_b128 v[190:193], v214 offset:32768
	s_waitcnt lgkmcnt(0)
	v_mfma_f32_32x32x16_bf16 v[2:17], v[186:189], v[190:193], v[2:17]
	ds_read_b128 v[186:189], v215
	ds_read_b128 v[190:193], v217 offset:32768
	s_waitcnt lgkmcnt(0)
	v_mfma_f32_32x32x16_bf16 v[2:17], v[186:189], v[190:193], v[2:17]
	ds_read_b128 v[186:189], v183
	ds_read_b128 v[190:193], v185 offset:32768
	v_lshl_add_u32 v185, v182, 2, s1
	v_mbcnt_lo_u32_b32 v183, -1, 0
	s_waitcnt lgkmcnt(0)
	s_barrier
	v_mfma_f32_32x32x16_bf16 v[2:17], v[186:189], v[190:193], v[2:17]
	s_nop 11
	ds_write2st64_b32 v185, v2, v3 offset1:1
	ds_write2st64_b32 v185, v4, v5 offset0:2 offset1:3
	ds_write2st64_b32 v185, v6, v7 offset0:4 offset1:5
	ds_write2st64_b32 v185, v8, v9 offset0:6 offset1:7
	ds_write2st64_b32 v185, v10, v11 offset0:8 offset1:9
	ds_write2st64_b32 v185, v12, v13 offset0:10 offset1:11
	ds_write2st64_b32 v185, v14, v15 offset0:12 offset1:13
	ds_write2st64_b32 v185, v16, v17 offset0:14 offset1:15
	s_waitcnt lgkmcnt(0)
	s_barrier
	s_cbranch_vccnz .LBB0_974
	v_mbcnt_hi_u32_b32 v12, -1, v183
	v_lshl_add_u32 v5, v182, 2, 0
	v_and_b32_e32 v6, 64, v12
	v_add_u32_e32 v13, 64, v6
	v_add_u32_e32 v6, s0, v5
	ds_read2st64_b32 v[8:9], v6 offset0:32 offset1:64
	ds_read_b32 v10, v185
	ds_read_b32 v14, v6 offset:24576
	v_xor_b32_e32 v4, 1, v12
	v_cmp_lt_i32_e32 vcc, v4, v13
	s_waitcnt lgkmcnt(0)
	v_mov_b32_e32 v11, v9
	v_xor_b32_e32 v7, 2, v12
	s_waitcnt lgkmcnt(0)
	v_mov_b32_e32 v9, v14
	v_pk_add_f32 v[8:9], v[10:11], v[8:9]
	v_cndmask_b32_e32 v4, v12, v4, vcc
	v_add_f32_e32 v8, v8, v9
	v_add_f32_e32 v14, v184, v8
	v_lshlrev_b32_e32 v4, 2, v4
	v_mul_f32_e32 v8, v14, v14
	s_nop 1
	v_mov_b32_dpp v9, v8 quad_perm:[1,0,3,2] row_mask:0xf bank_mask:0xf
	v_cmp_lt_i32_e32 vcc, v7, v13
	v_xor_b32_e32 v8, 8, v12
	v_xor_b32_e32 v11, 16, v12
	v_cndmask_b32_e32 v5, v12, v7, vcc
	v_lshlrev_b32_e32 v5, 2, v5
	s_waitcnt lgkmcnt(0)
	v_fmac_f32_e32 v9, v14, v14
	v_xor_b32_e32 v7, 4, v12
	v_cmp_lt_i32_e32 vcc, v7, v13
	v_or_b32_e32 v2, s13, v181
	s_lshl_b32 s0, s33, 2
	v_cndmask_b32_e32 v7, v12, v7, vcc
	v_lshlrev_b32_e32 v7, 2, v7
	s_waitcnt lgkmcnt(0)
	v_add_f32_dpp v10, v9, v9 quad_perm:[2,3,0,1] row_mask:0xf bank_mask:0xf
	v_cmp_lt_i32_e32 vcc, v8, v13
	s_lshl_b32 s1, s11, 3
	v_or_b32_e32 v178, s12, v2
	v_cndmask_b32_e32 v8, v12, v8, vcc
	v_lshlrev_b32_e32 v8, 2, v8
	v_cmp_lt_i32_e32 vcc, v11, v13
	s_waitcnt lgkmcnt(0)
	v_add_f32_dpp v10, v10, v10 row_half_mirror row_mask:0xf bank_mask:0xf
	s_or_b32 s0, s1, s0
	v_cndmask_b32_e32 v9, v12, v11, vcc
	v_lshlrev_b32_e32 v9, 2, v9
	v_lshl_add_u64 v[2:3], v[178:179], 2, s[8:9]
	s_add_u32 s0, s31, s0
	v_lshlrev_b64 v[12:13], 12, v[176:177]
	s_waitcnt lgkmcnt(0)
	v_add_f32_dpp v10, v10, v10 row_mirror row_mask:0xf bank_mask:0xf
	v_mov_b32_e32 v11, v10
	s_nop 1
	v_permlane16_swap_b32_e32 v11, v10
	v_cmp_eq_u32_e32 vcc, 0, v181
	s_addc_u32 s1, s40, 0
	v_lshl_add_u64 v[12:13], v[2:3], 0, v[12:13]
	global_store_dword v[12:13], v14, off sc1
	s_and_saveexec_b64 s[2:3], vcc
	s_cbranch_execz .LBB0_943
	s_waitcnt lgkmcnt(0)
	v_add_f32_e32 v12, v10, v11
	v_lshlrev_b64 v[10:11], 7, v[176:177]
	v_lshl_add_u64 v[10:11], s[0:1], 0, v[10:11]
	global_store_dword v[10:11], v12, off sc1
.LBB0_943:
	s_or_b64 exec, exec, s[2:3]
	s_waitcnt lgkmcnt(0)
	ds_read2st64_b32 v[10:11], v6 offset0:33 offset1:65
	ds_read_b32 v14, v6 offset:24832
	ds_read_b32 v12, v185 offset:256
	s_waitcnt lgkmcnt(0)
	v_mov_b32_e32 v13, v11
	s_waitcnt lgkmcnt(0)
	v_mov_b32_e32 v11, v14
	s_waitcnt lgkmcnt(0)
	v_pk_add_f32 v[10:11], v[12:13], v[10:11]
	s_nop 0
	v_add_f32_e32 v10, v10, v11
	v_add_f32_e32 v14, v169, v10
	v_mul_f32_e32 v10, v14, v14
	s_nop 1
	v_mov_b32_dpp v10, v10 quad_perm:[1,0,3,2] row_mask:0xf bank_mask:0xf
	v_ashrrev_i32_e32 v169, 31, v168
	v_lshlrev_b64 v[12:13], 12, v[168:169]
	v_lshl_add_u64 v[12:13], v[2:3], 0, v[12:13]
	global_store_dword v[12:13], v14, off sc1
	s_waitcnt lgkmcnt(0)
	v_fmac_f32_e32 v10, v14, v14
	s_waitcnt lgkmcnt(0)
	s_nop 0
	v_add_f32_dpp v10, v10, v10 quad_perm:[2,3,0,1] row_mask:0xf bank_mask:0xf
	s_waitcnt lgkmcnt(0)
	s_nop 0
	v_add_f32_dpp v10, v10, v10 row_half_mirror row_mask:0xf bank_mask:0xf
	s_waitcnt lgkmcnt(0)
	s_nop 0
	v_add_f32_dpp v10, v10, v10 row_mirror row_mask:0xf bank_mask:0xf
	v_mov_b32_e32 v11, v10
	s_nop 1
	v_permlane16_swap_b32_e32 v11, v10
	s_and_saveexec_b64 s[2:3], vcc
	s_cbranch_execz .LBB0_945
	s_waitcnt lgkmcnt(0)
	v_add_f32_e32 v12, v10, v11
	v_lshlrev_b64 v[10:11], 7, v[168:169]
	v_lshl_add_u64 v[10:11], s[0:1], 0, v[10:11]
	global_store_dword v[10:11], v12, off sc1
; DI int crow(int r, int hi) { return (r & 3) + 8 * (r >> 2) + 4 * hi; }
; template <class EpiT> ...
;     ...
;         for (int i = 0; i < 16; ++i) {
;             const float v0 = (part[(wave * 16 + i) * 64 + lane] + part[((wave + 2) * 16 + i) * 64 + lane]) + (part[((wave + 4) * 16 + i) * 64 + lane] + part[((wave + 6) * 16 + i) * 64 + lane]);
;             const int row = 32 * rt + crow(i, hh), col = 64 * cp + 32 * wave + r32, ct = 2 * cp + wave;
;             const float v = v0 + xv[i];
;             __hip_atomic_store((unsigned*)(XS2 + (size_t)row * D + col), __float_as_uint(v), __ATOMIC_RELAXED, __HIP_MEMORY_SCOPE_AGENT);
;             float q = v * v; q += __shfl_xor(q, 1); q += __shfl_xor(q, 2); q += __shfl_xor(q, 4); q += __shfl_xor(q, 8); q += __shfl_xor(q, 16);
;             if (r32 == 0) __hip_atomic_store((unsigned*)(SSQ + (size_t)row * 32 + ct), __float_as_uint(q), __ATOMIC_RELAXED, __HIP_MEMORY_SCOPE_AGENT);
;         }
.LBB0_945:
	s_or_b64 exec, exec, s[2:3]
	s_waitcnt lgkmcnt(0)
	ds_read2st64_b32 v[10:11], v6 offset0:34 offset1:66
	ds_read_b32 v14, v6 offset:25088
	ds_read_b32 v12, v185 offset:512
	s_waitcnt lgkmcnt(0)
	v_mov_b32_e32 v13, v11
	s_waitcnt lgkmcnt(0)
	v_mov_b32_e32 v11, v14
	s_waitcnt lgkmcnt(0)
	v_pk_add_f32 v[10:11], v[12:13], v[10:11]
	s_nop 0
	v_add_f32_e32 v10, v10, v11
	v_add_f32_e32 v14, v175, v10
	v_mul_f32_e32 v10, v14, v14
	s_nop 1
	v_mov_b32_dpp v10, v10 quad_perm:[1,0,3,2] row_mask:0xf bank_mask:0xf
	v_ashrrev_i32_e32 v175, 31, v174
	v_lshlrev_b64 v[12:13], 12, v[174:175]
	v_lshl_add_u64 v[12:13], v[2:3], 0, v[12:13]
	global_store_dword v[12:13], v14, off sc1
	s_waitcnt lgkmcnt(0)
	v_fmac_f32_e32 v10, v14, v14
	s_waitcnt lgkmcnt(0)
	s_nop 0
	v_add_f32_dpp v10, v10, v10 quad_perm:[2,3,0,1] row_mask:0xf bank_mask:0xf
	s_waitcnt lgkmcnt(0)
	s_nop 0
	v_add_f32_dpp v10, v10, v10 row_half_mirror row_mask:0xf bank_mask:0xf
	s_waitcnt lgkmcnt(0)
	s_nop 0
	v_add_f32_dpp v10, v10, v10 row_mirror row_mask:0xf bank_mask:0xf
	v_mov_b32_e32 v11, v10
	s_nop 1
	v_permlane16_swap_b32_e32 v11, v10
	s_and_saveexec_b64 s[2:3], vcc
	s_cbranch_execz .LBB0_947
	s_waitcnt lgkmcnt(0)
	v_add_f32_e32 v12, v10, v11
	v_lshlrev_b64 v[10:11], 7, v[174:175]
	v_lshl_add_u64 v[10:11], s[0:1], 0, v[10:11]
	global_store_dword v[10:11], v12, off sc1
.LBB0_947:
	s_or_b64 exec, exec, s[2:3]
	s_waitcnt lgkmcnt(0)
	ds_read2st64_b32 v[10:11], v6 offset0:35 offset1:67
	ds_read_b32 v14, v6 offset:25344
	ds_read_b32 v12, v185 offset:768
	s_waitcnt lgkmcnt(0)
	v_mov_b32_e32 v13, v11
	s_waitcnt lgkmcnt(0)
	v_mov_b32_e32 v11, v14
	s_waitcnt lgkmcnt(0)
	v_pk_add_f32 v[10:11], v[12:13], v[10:11]
	s_nop 0
	v_add_f32_e32 v10, v10, v11
	v_add_f32_e32 v14, v173, v10
	v_mul_f32_e32 v10, v14, v14
	s_nop 1
	v_mov_b32_dpp v10, v10 quad_perm:[1,0,3,2] row_mask:0xf bank_mask:0xf
	v_ashrrev_i32_e32 v173, 31, v172
	v_lshlrev_b64 v[12:13], 12, v[172:173]
	v_lshl_add_u64 v[12:13], v[2:3], 0, v[12:13]
	global_store_dword v[12:13], v14, off sc1
	s_waitcnt lgkmcnt(0)
	v_fmac_f32_e32 v10, v14, v14
	s_waitcnt lgkmcnt(0)
	s_nop 0
	v_add_f32_dpp v10, v10, v10 quad_perm:[2,3,0,1] row_mask:0xf bank_mask:0xf
	s_waitcnt lgkmcnt(0)
	s_nop 0
	v_add_f32_dpp v10, v10, v10 row_half_mirror row_mask:0xf bank_mask:0xf
	s_waitcnt lgkmcnt(0)
	s_nop 0
	v_add_f32_dpp v10, v10, v10 row_mirror row_mask:0xf bank_mask:0xf
	v_mov_b32_e32 v11, v10
	s_nop 1
	v_permlane16_swap_b32_e32 v11, v10
	s_and_saveexec_b64 s[2:3], vcc
	s_cbranch_execz .LBB0_949
	s_waitcnt lgkmcnt(0)
	v_add_f32_e32 v12, v10, v11
	v_lshlrev_b64 v[10:11], 7, v[172:173]
	v_lshl_add_u64 v[10:11], s[0:1], 0, v[10:11]
	global_store_dword v[10:11], v12, off sc1
.LBB0_949:
	s_or_b64 exec, exec, s[2:3]
	s_waitcnt lgkmcnt(0)
	ds_read2st64_b32 v[10:11], v6 offset0:36 offset1:68
	ds_read_b32 v14, v6 offset:25600
	ds_read_b32 v12, v185 offset:1024
	s_waitcnt lgkmcnt(0)
	v_mov_b32_e32 v13, v11
	s_waitcnt lgkmcnt(0)
	v_mov_b32_e32 v11, v14
	s_waitcnt lgkmcnt(0)
	v_pk_add_f32 v[10:11], v[12:13], v[10:11]
	s_nop 0
	v_add_f32_e32 v10, v10, v11
	v_add_f32_e32 v14, v171, v10
	v_mul_f32_e32 v10, v14, v14
	s_nop 1
	v_mov_b32_dpp v10, v10 quad_perm:[1,0,3,2] row_mask:0xf bank_mask:0xf
	v_ashrrev_i32_e32 v171, 31, v170
	v_lshlrev_b64 v[12:13], 12, v[170:171]
	v_lshl_add_u64 v[12:13], v[2:3], 0, v[12:13]
	global_store_dword v[12:13], v14, off sc1
	s_waitcnt lgkmcnt(0)
	v_fmac_f32_e32 v10, v14, v14
	s_waitcnt lgkmcnt(0)
	s_nop 0
	v_add_f32_dpp v10, v10, v10 quad_perm:[2,3,0,1] row_mask:0xf bank_mask:0xf
	s_waitcnt lgkmcnt(0)
	s_nop 0
	v_add_f32_dpp v10, v10, v10 row_half_mirror row_mask:0xf bank_mask:0xf
	s_waitcnt lgkmcnt(0)
	s_nop 0
	v_add_f32_dpp v10, v10, v10 row_mirror row_mask:0xf bank_mask:0xf
	v_mov_b32_e32 v11, v10
	s_nop 1
	v_permlane16_swap_b32_e32 v11, v10
	s_and_saveexec_b64 s[2:3], vcc
	s_cbranch_execz .LBB0_951
	s_waitcnt lgkmcnt(0)
	v_add_f32_e32 v12, v10, v11
	v_lshlrev_b64 v[10:11], 7, v[170:171]
	v_lshl_add_u64 v[10:11], s[0:1], 0, v[10:11]
	global_store_dword v[10:11], v12, off sc1
.LBB0_951:
	s_or_b64 exec, exec, s[2:3]
	s_waitcnt lgkmcnt(0)
	ds_read2st64_b32 v[10:11], v6 offset0:37 offset1:69
	ds_read_b32 v14, v6 offset:25856
	ds_read_b32 v12, v185 offset:1280
	s_waitcnt lgkmcnt(0)
	v_mov_b32_e32 v13, v11
	s_waitcnt lgkmcnt(0)
	v_mov_b32_e32 v11, v14
	s_waitcnt lgkmcnt(0)
	v_pk_add_f32 v[10:11], v[12:13], v[10:11]
	s_nop 0
	v_add_f32_e32 v10, v10, v11
	v_add_f32_e32 v14, v167, v10
	v_mul_f32_e32 v10, v14, v14
	s_nop 1
	v_mov_b32_dpp v10, v10 quad_perm:[1,0,3,2] row_mask:0xf bank_mask:0xf
	v_ashrrev_i32_e32 v167, 31, v166
	v_lshlrev_b64 v[12:13], 12, v[166:167]
	v_lshl_add_u64 v[12:13], v[2:3], 0, v[12:13]
	global_store_dword v[12:13], v14, off sc1
	s_waitcnt lgkmcnt(0)
	v_fmac_f32_e32 v10, v14, v14
	s_waitcnt lgkmcnt(0)
	s_nop 0
	v_add_f32_dpp v10, v10, v10 quad_perm:[2,3,0,1] row_mask:0xf bank_mask:0xf
	s_waitcnt lgkmcnt(0)
	s_nop 0
	v_add_f32_dpp v10, v10, v10 row_half_mirror row_mask:0xf bank_mask:0xf
	s_waitcnt lgkmcnt(0)
	s_nop 0
	v_add_f32_dpp v10, v10, v10 row_mirror row_mask:0xf bank_mask:0xf
	v_mov_b32_e32 v11, v10
	s_nop 1
	v_permlane16_swap_b32_e32 v11, v10
	s_and_saveexec_b64 s[2:3], vcc
	s_cbranch_execz .LBB0_953
	s_waitcnt lgkmcnt(0)
	v_add_f32_e32 v12, v10, v11
	v_lshlrev_b64 v[10:11], 7, v[166:167]
	v_lshl_add_u64 v[10:11], s[0:1], 0, v[10:11]
	global_store_dword v[10:11], v12, off sc1
; DI int crow(int r, int hi) { return (r & 3) + 8 * (r >> 2) + 4 * hi; }
; template <class EpiT> ...
;     ...
;         for (int i = 0; i < 16; ++i) {
;             const float v0 = (part[(wave * 16 + i) * 64 + lane] + part[((wave + 2) * 16 + i) * 64 + lane]) + (part[((wave + 4) * 16 + i) * 64 + lane] + part[((wave + 6) * 16 + i) * 64 + lane]);
;             const int row = 32 * rt + crow(i, hh), col = 64 * cp + 32 * wave + r32, ct = 2 * cp + wave;
;             const float v = v0 + xv[i];
;             __hip_atomic_store((unsigned*)(XS2 + (size_t)row * D + col), __float_as_uint(v), __ATOMIC_RELAXED, __HIP_MEMORY_SCOPE_AGENT);
;             float q = v * v; q += __shfl_xor(q, 1); q += __shfl_xor(q, 2); q += __shfl_xor(q, 4); q += __shfl_xor(q, 8); q += __shfl_xor(q, 16);
;             if (r32 == 0) __hip_atomic_store((unsigned*)(SSQ + (size_t)row * 32 + ct), __float_as_uint(q), __ATOMIC_RELAXED, __HIP_MEMORY_SCOPE_AGENT);
;         }
.LBB0_953:
	s_or_b64 exec, exec, s[2:3]
	s_waitcnt lgkmcnt(0)
	ds_read2st64_b32 v[10:11], v6 offset0:38 offset1:70
	ds_read_b32 v14, v6 offset:26112
	ds_read_b32 v12, v185 offset:1536
	s_waitcnt lgkmcnt(0)
	v_mov_b32_e32 v13, v11
	s_waitcnt lgkmcnt(0)
	v_mov_b32_e32 v11, v14
	s_waitcnt lgkmcnt(0)
	v_pk_add_f32 v[10:11], v[12:13], v[10:11]
	s_nop 0
	v_add_f32_e32 v10, v10, v11
	v_add_f32_e32 v14, v165, v10
	v_mul_f32_e32 v10, v14, v14
	s_nop 1
	v_mov_b32_dpp v10, v10 quad_perm:[1,0,3,2] row_mask:0xf bank_mask:0xf
	v_ashrrev_i32_e32 v165, 31, v164
	v_lshlrev_b64 v[12:13], 12, v[164:165]
	v_lshl_add_u64 v[12:13], v[2:3], 0, v[12:13]
	global_store_dword v[12:13], v14, off sc1
	s_waitcnt lgkmcnt(0)
	v_fmac_f32_e32 v10, v14, v14
	s_waitcnt lgkmcnt(0)
	s_nop 0
	v_add_f32_dpp v10, v10, v10 quad_perm:[2,3,0,1] row_mask:0xf bank_mask:0xf
	s_waitcnt lgkmcnt(0)
	s_nop 0
	v_add_f32_dpp v10, v10, v10 row_half_mirror row_mask:0xf bank_mask:0xf
	s_waitcnt lgkmcnt(0)
	s_nop 0
	v_add_f32_dpp v10, v10, v10 row_mirror row_mask:0xf bank_mask:0xf
	v_mov_b32_e32 v11, v10
	s_nop 1
	v_permlane16_swap_b32_e32 v11, v10
	s_and_saveexec_b64 s[2:3], vcc
	s_cbranch_execz .LBB0_955
	s_waitcnt lgkmcnt(0)
	v_add_f32_e32 v12, v10, v11
	v_lshlrev_b64 v[10:11], 7, v[164:165]
	v_lshl_add_u64 v[10:11], s[0:1], 0, v[10:11]
	global_store_dword v[10:11], v12, off sc1
.LBB0_955:
	s_or_b64 exec, exec, s[2:3]
	s_waitcnt lgkmcnt(0)
	ds_read2st64_b32 v[10:11], v6 offset0:39 offset1:71
	ds_read_b32 v14, v6 offset:26368
	ds_read_b32 v12, v185 offset:1792
	s_waitcnt lgkmcnt(0)
	v_mov_b32_e32 v13, v11
	s_waitcnt lgkmcnt(0)
	v_mov_b32_e32 v11, v14
	s_waitcnt lgkmcnt(0)
	v_pk_add_f32 v[10:11], v[12:13], v[10:11]
	s_nop 0
	v_add_f32_e32 v10, v10, v11
	v_add_f32_e32 v14, v163, v10
	v_mul_f32_e32 v10, v14, v14
	s_nop 1
	v_mov_b32_dpp v10, v10 quad_perm:[1,0,3,2] row_mask:0xf bank_mask:0xf
	v_ashrrev_i32_e32 v163, 31, v162
	v_lshlrev_b64 v[12:13], 12, v[162:163]
	v_lshl_add_u64 v[12:13], v[2:3], 0, v[12:13]
	global_store_dword v[12:13], v14, off sc1
	s_waitcnt lgkmcnt(0)
	v_fmac_f32_e32 v10, v14, v14
	s_waitcnt lgkmcnt(0)
	s_nop 0
	v_add_f32_dpp v10, v10, v10 quad_perm:[2,3,0,1] row_mask:0xf bank_mask:0xf
	s_waitcnt lgkmcnt(0)
	s_nop 0
	v_add_f32_dpp v10, v10, v10 row_half_mirror row_mask:0xf bank_mask:0xf
	s_waitcnt lgkmcnt(0)
	s_nop 0
	v_add_f32_dpp v10, v10, v10 row_mirror row_mask:0xf bank_mask:0xf
	v_mov_b32_e32 v11, v10
	s_nop 1
	v_permlane16_swap_b32_e32 v11, v10
	s_and_saveexec_b64 s[2:3], vcc
	s_cbranch_execz .LBB0_957
	s_waitcnt lgkmcnt(0)
	v_add_f32_e32 v12, v10, v11
	v_lshlrev_b64 v[10:11], 7, v[162:163]
	v_lshl_add_u64 v[10:11], s[0:1], 0, v[10:11]
	global_store_dword v[10:11], v12, off sc1
.LBB0_957:
	s_or_b64 exec, exec, s[2:3]
	s_waitcnt lgkmcnt(0)
	ds_read2st64_b32 v[10:11], v6 offset0:40 offset1:72
	ds_read_b32 v14, v6 offset:26624
	ds_read_b32 v12, v185 offset:2048
	s_waitcnt lgkmcnt(0)
	v_mov_b32_e32 v13, v11
	s_waitcnt lgkmcnt(0)
	v_mov_b32_e32 v11, v14
	s_waitcnt lgkmcnt(0)
	v_pk_add_f32 v[10:11], v[12:13], v[10:11]
	s_nop 0
	v_add_f32_e32 v10, v10, v11
	v_add_f32_e32 v14, v161, v10
	v_mul_f32_e32 v10, v14, v14
	s_nop 1
	v_mov_b32_dpp v10, v10 quad_perm:[1,0,3,2] row_mask:0xf bank_mask:0xf
	v_ashrrev_i32_e32 v161, 31, v160
	v_lshlrev_b64 v[12:13], 12, v[160:161]
	v_lshl_add_u64 v[12:13], v[2:3], 0, v[12:13]
	global_store_dword v[12:13], v14, off sc1
	s_waitcnt lgkmcnt(0)
	v_fmac_f32_e32 v10, v14, v14
	s_waitcnt lgkmcnt(0)
	s_nop 0
	v_add_f32_dpp v10, v10, v10 quad_perm:[2,3,0,1] row_mask:0xf bank_mask:0xf
	s_waitcnt lgkmcnt(0)
	s_nop 0
	v_add_f32_dpp v10, v10, v10 row_half_mirror row_mask:0xf bank_mask:0xf
	s_waitcnt lgkmcnt(0)
	s_nop 0
	v_add_f32_dpp v10, v10, v10 row_mirror row_mask:0xf bank_mask:0xf
	v_mov_b32_e32 v11, v10
	s_nop 1
	v_permlane16_swap_b32_e32 v11, v10
	s_and_saveexec_b64 s[2:3], vcc
	s_cbranch_execz .LBB0_959
	s_waitcnt lgkmcnt(0)
	v_add_f32_e32 v12, v10, v11
	v_lshlrev_b64 v[10:11], 7, v[160:161]
	v_lshl_add_u64 v[10:11], s[0:1], 0, v[10:11]
	global_store_dword v[10:11], v12, off sc1
.LBB0_959:
	s_or_b64 exec, exec, s[2:3]
	s_waitcnt lgkmcnt(0)
	ds_read2st64_b32 v[10:11], v6 offset0:41 offset1:73
	ds_read_b32 v14, v6 offset:26880
	ds_read_b32 v12, v185 offset:2304
	s_waitcnt lgkmcnt(0)
	v_mov_b32_e32 v13, v11
	s_waitcnt lgkmcnt(0)
	v_mov_b32_e32 v11, v14
	s_waitcnt lgkmcnt(0)
	v_pk_add_f32 v[10:11], v[12:13], v[10:11]
	s_nop 0
	v_add_f32_e32 v10, v10, v11
	v_add_f32_e32 v14, v159, v10
	v_mul_f32_e32 v10, v14, v14
	s_nop 1
	v_mov_b32_dpp v10, v10 quad_perm:[1,0,3,2] row_mask:0xf bank_mask:0xf
	v_ashrrev_i32_e32 v159, 31, v158
	v_lshlrev_b64 v[12:13], 12, v[158:159]
	v_lshl_add_u64 v[12:13], v[2:3], 0, v[12:13]
	global_store_dword v[12:13], v14, off sc1
	s_waitcnt lgkmcnt(0)
	v_fmac_f32_e32 v10, v14, v14
	s_waitcnt lgkmcnt(0)
	s_nop 0
	v_add_f32_dpp v10, v10, v10 quad_perm:[2,3,0,1] row_mask:0xf bank_mask:0xf
	s_waitcnt lgkmcnt(0)
	s_nop 0
	v_add_f32_dpp v10, v10, v10 row_half_mirror row_mask:0xf bank_mask:0xf
	s_waitcnt lgkmcnt(0)
	s_nop 0
	v_add_f32_dpp v10, v10, v10 row_mirror row_mask:0xf bank_mask:0xf
	v_mov_b32_e32 v11, v10
	s_nop 1
	v_permlane16_swap_b32_e32 v11, v10
	s_and_saveexec_b64 s[2:3], vcc
	s_cbranch_execz .LBB0_961
	s_waitcnt lgkmcnt(0)
	v_add_f32_e32 v12, v10, v11
	v_lshlrev_b64 v[10:11], 7, v[158:159]
	v_lshl_add_u64 v[10:11], s[0:1], 0, v[10:11]
	global_store_dword v[10:11], v12, off sc1
; DI int crow(int r, int hi) { return (r & 3) + 8 * (r >> 2) + 4 * hi; }
; template <class EpiT> ...
;     ...
;         for (int i = 0; i < 16; ++i) {
;             const float v0 = (part[(wave * 16 + i) * 64 + lane] + part[((wave + 2) * 16 + i) * 64 + lane]) + (part[((wave + 4) * 16 + i) * 64 + lane] + part[((wave + 6) * 16 + i) * 64 + lane]);
;             const int row = 32 * rt + crow(i, hh), col = 64 * cp + 32 * wave + r32, ct = 2 * cp + wave;
;             const float v = v0 + xv[i];
;             __hip_atomic_store((unsigned*)(XS2 + (size_t)row * D + col), __float_as_uint(v), __ATOMIC_RELAXED, __HIP_MEMORY_SCOPE_AGENT);
;             float q = v * v; q += __shfl_xor(q, 1); q += __shfl_xor(q, 2); q += __shfl_xor(q, 4); q += __shfl_xor(q, 8); q += __shfl_xor(q, 16);
;             if (r32 == 0) __hip_atomic_store((unsigned*)(SSQ + (size_t)row * 32 + ct), __float_as_uint(q), __ATOMIC_RELAXED, __HIP_MEMORY_SCOPE_AGENT);
;         }
.LBB0_961:
	s_or_b64 exec, exec, s[2:3]
	s_waitcnt lgkmcnt(0)
	ds_read2st64_b32 v[10:11], v6 offset0:42 offset1:74
	ds_read_b32 v14, v6 offset:27136
	ds_read_b32 v12, v185 offset:2560
	s_waitcnt lgkmcnt(0)
	v_mov_b32_e32 v13, v11
	s_waitcnt lgkmcnt(0)
	v_mov_b32_e32 v11, v14
	s_waitcnt lgkmcnt(0)
	v_pk_add_f32 v[10:11], v[12:13], v[10:11]
	s_nop 0
	v_add_f32_e32 v10, v10, v11
	v_add_f32_e32 v14, v157, v10
	v_mul_f32_e32 v10, v14, v14
	s_nop 1
	v_mov_b32_dpp v10, v10 quad_perm:[1,0,3,2] row_mask:0xf bank_mask:0xf
	v_ashrrev_i32_e32 v157, 31, v156
	v_lshlrev_b64 v[12:13], 12, v[156:157]
	v_lshl_add_u64 v[12:13], v[2:3], 0, v[12:13]
	global_store_dword v[12:13], v14, off sc1
	s_waitcnt lgkmcnt(0)
	v_fmac_f32_e32 v10, v14, v14
	s_waitcnt lgkmcnt(0)
	s_nop 0
	v_add_f32_dpp v10, v10, v10 quad_perm:[2,3,0,1] row_mask:0xf bank_mask:0xf
	s_waitcnt lgkmcnt(0)
	s_nop 0
	v_add_f32_dpp v10, v10, v10 row_half_mirror row_mask:0xf bank_mask:0xf
	s_waitcnt lgkmcnt(0)
	s_nop 0
	v_add_f32_dpp v10, v10, v10 row_mirror row_mask:0xf bank_mask:0xf
	v_mov_b32_e32 v11, v10
	s_nop 1
	v_permlane16_swap_b32_e32 v11, v10
	s_and_saveexec_b64 s[2:3], vcc
	s_cbranch_execz .LBB0_963
	s_waitcnt lgkmcnt(0)
	v_add_f32_e32 v12, v10, v11
	v_lshlrev_b64 v[10:11], 7, v[156:157]
	v_lshl_add_u64 v[10:11], s[0:1], 0, v[10:11]
	global_store_dword v[10:11], v12, off sc1
.LBB0_963:
	s_or_b64 exec, exec, s[2:3]
	s_waitcnt lgkmcnt(0)
	ds_read2st64_b32 v[10:11], v6 offset0:43 offset1:75
	ds_read_b32 v14, v6 offset:27392
	ds_read_b32 v12, v185 offset:2816
	s_waitcnt lgkmcnt(0)
	v_mov_b32_e32 v13, v11
	s_waitcnt lgkmcnt(0)
	v_mov_b32_e32 v11, v14
	s_waitcnt lgkmcnt(0)
	v_pk_add_f32 v[10:11], v[12:13], v[10:11]
	s_nop 0
	v_add_f32_e32 v10, v10, v11
	v_add_f32_e32 v14, v155, v10
	v_mul_f32_e32 v10, v14, v14
	s_nop 1
	v_mov_b32_dpp v10, v10 quad_perm:[1,0,3,2] row_mask:0xf bank_mask:0xf
	v_ashrrev_i32_e32 v155, 31, v154
	v_lshlrev_b64 v[12:13], 12, v[154:155]
	v_lshl_add_u64 v[12:13], v[2:3], 0, v[12:13]
	global_store_dword v[12:13], v14, off sc1
	s_waitcnt lgkmcnt(0)
	v_fmac_f32_e32 v10, v14, v14
	s_waitcnt lgkmcnt(0)
	s_nop 0
	v_add_f32_dpp v10, v10, v10 quad_perm:[2,3,0,1] row_mask:0xf bank_mask:0xf
	s_waitcnt lgkmcnt(0)
	s_nop 0
	v_add_f32_dpp v10, v10, v10 row_half_mirror row_mask:0xf bank_mask:0xf
	s_waitcnt lgkmcnt(0)
	s_nop 0
	v_add_f32_dpp v10, v10, v10 row_mirror row_mask:0xf bank_mask:0xf
	v_mov_b32_e32 v11, v10
	s_nop 1
	v_permlane16_swap_b32_e32 v11, v10
	s_and_saveexec_b64 s[2:3], vcc
	s_cbranch_execz .LBB0_965
	s_waitcnt lgkmcnt(0)
	v_add_f32_e32 v12, v10, v11
	v_lshlrev_b64 v[10:11], 7, v[154:155]
	v_lshl_add_u64 v[10:11], s[0:1], 0, v[10:11]
	global_store_dword v[10:11], v12, off sc1
.LBB0_965:
	s_or_b64 exec, exec, s[2:3]
	s_waitcnt lgkmcnt(0)
	ds_read2st64_b32 v[10:11], v6 offset0:44 offset1:76
	ds_read_b32 v14, v6 offset:27648
	ds_read_b32 v12, v185 offset:3072
	s_waitcnt lgkmcnt(0)
	v_mov_b32_e32 v13, v11
	s_waitcnt lgkmcnt(0)
	v_mov_b32_e32 v11, v14
	s_waitcnt lgkmcnt(0)
	v_pk_add_f32 v[10:11], v[12:13], v[10:11]
	s_nop 0
	v_add_f32_e32 v10, v10, v11
	v_add_f32_e32 v14, v153, v10
	v_mul_f32_e32 v10, v14, v14
	s_nop 1
	v_mov_b32_dpp v10, v10 quad_perm:[1,0,3,2] row_mask:0xf bank_mask:0xf
	v_ashrrev_i32_e32 v153, 31, v152
	v_lshlrev_b64 v[12:13], 12, v[152:153]
	v_lshl_add_u64 v[12:13], v[2:3], 0, v[12:13]
	global_store_dword v[12:13], v14, off sc1
	s_waitcnt lgkmcnt(0)
	v_fmac_f32_e32 v10, v14, v14
	s_waitcnt lgkmcnt(0)
	s_nop 0
	v_add_f32_dpp v10, v10, v10 quad_perm:[2,3,0,1] row_mask:0xf bank_mask:0xf
	s_waitcnt lgkmcnt(0)
	s_nop 0
	v_add_f32_dpp v10, v10, v10 row_half_mirror row_mask:0xf bank_mask:0xf
	s_waitcnt lgkmcnt(0)
	s_nop 0
	v_add_f32_dpp v10, v10, v10 row_mirror row_mask:0xf bank_mask:0xf
	v_mov_b32_e32 v11, v10
	s_nop 1
	v_permlane16_swap_b32_e32 v11, v10
	s_and_saveexec_b64 s[2:3], vcc
	s_cbranch_execz .LBB0_967
	s_waitcnt lgkmcnt(0)
	v_add_f32_e32 v12, v10, v11
	v_lshlrev_b64 v[10:11], 7, v[152:153]
	v_lshl_add_u64 v[10:11], s[0:1], 0, v[10:11]
	global_store_dword v[10:11], v12, off sc1
; DI int crow(int r, int hi) { return (r & 3) + 8 * (r >> 2) + 4 * hi; }
; template <class EpiT> ...
;     ...
;         for (int i = 0; i < 16; ++i) {
;             const float v0 = (part[(wave * 16 + i) * 64 + lane] + part[((wave + 2) * 16 + i) * 64 + lane]) + (part[((wave + 4) * 16 + i) * 64 + lane] + part[((wave + 6) * 16 + i) * 64 + lane]);
;             const int row = 32 * rt + crow(i, hh), col = 64 * cp + 32 * wave + r32, ct = 2 * cp + wave;
;             const float v = v0 + xv[i];
;             __hip_atomic_store((unsigned*)(XS2 + (size_t)row * D + col), __float_as_uint(v), __ATOMIC_RELAXED, __HIP_MEMORY_SCOPE_AGENT);
;             float q = v * v; q += __shfl_xor(q, 1); q += __shfl_xor(q, 2); q += __shfl_xor(q, 4); q += __shfl_xor(q, 8); q += __shfl_xor(q, 16);
;             if (r32 == 0) __hip_atomic_store((unsigned*)(SSQ + (size_t)row * 32 + ct), __float_as_uint(q), __ATOMIC_RELAXED, __HIP_MEMORY_SCOPE_AGENT);
;         }
.LBB0_967:
	s_or_b64 exec, exec, s[2:3]
	s_waitcnt lgkmcnt(0)
	ds_read2st64_b32 v[10:11], v6 offset0:45 offset1:77
	ds_read_b32 v14, v6 offset:27904
	ds_read_b32 v12, v185 offset:3328
	s_waitcnt lgkmcnt(0)
	v_mov_b32_e32 v13, v11
	s_waitcnt lgkmcnt(0)
	v_mov_b32_e32 v11, v14
	s_waitcnt lgkmcnt(0)
	v_pk_add_f32 v[10:11], v[12:13], v[10:11]
	s_nop 0
	v_add_f32_e32 v10, v10, v11
	v_add_f32_e32 v14, v151, v10
	v_mul_f32_e32 v10, v14, v14
	s_nop 1
	v_mov_b32_dpp v10, v10 quad_perm:[1,0,3,2] row_mask:0xf bank_mask:0xf
	v_ashrrev_i32_e32 v151, 31, v150
	v_lshlrev_b64 v[12:13], 12, v[150:151]
	v_lshl_add_u64 v[12:13], v[2:3], 0, v[12:13]
	global_store_dword v[12:13], v14, off sc1
	s_waitcnt lgkmcnt(0)
	v_fmac_f32_e32 v10, v14, v14
	s_waitcnt lgkmcnt(0)
	s_nop 0
	v_add_f32_dpp v10, v10, v10 quad_perm:[2,3,0,1] row_mask:0xf bank_mask:0xf
	s_waitcnt lgkmcnt(0)
	s_nop 0
	v_add_f32_dpp v10, v10, v10 row_half_mirror row_mask:0xf bank_mask:0xf
	s_waitcnt lgkmcnt(0)
	s_nop 0
	v_add_f32_dpp v10, v10, v10 row_mirror row_mask:0xf bank_mask:0xf
	v_mov_b32_e32 v11, v10
	s_nop 1
	v_permlane16_swap_b32_e32 v11, v10
	s_and_saveexec_b64 s[2:3], vcc
	s_cbranch_execz .LBB0_969
	s_waitcnt lgkmcnt(0)
	v_add_f32_e32 v12, v10, v11
	v_lshlrev_b64 v[10:11], 7, v[150:151]
	v_lshl_add_u64 v[10:11], s[0:1], 0, v[10:11]
	global_store_dword v[10:11], v12, off sc1
.LBB0_969:
	s_or_b64 exec, exec, s[2:3]
	s_waitcnt lgkmcnt(0)
	ds_read2st64_b32 v[10:11], v6 offset0:46 offset1:78
	ds_read_b32 v14, v6 offset:28160
	ds_read_b32 v12, v185 offset:3584
	s_waitcnt lgkmcnt(0)
	v_mov_b32_e32 v13, v11
	s_waitcnt lgkmcnt(0)
	v_mov_b32_e32 v11, v14
	s_waitcnt lgkmcnt(0)
	v_pk_add_f32 v[10:11], v[12:13], v[10:11]
	s_nop 0
	v_add_f32_e32 v10, v10, v11
	v_add_f32_e32 v14, v149, v10
	v_mul_f32_e32 v10, v14, v14
	s_nop 1
	v_mov_b32_dpp v10, v10 quad_perm:[1,0,3,2] row_mask:0xf bank_mask:0xf
	v_ashrrev_i32_e32 v149, 31, v148
	v_lshlrev_b64 v[12:13], 12, v[148:149]
	v_lshl_add_u64 v[12:13], v[2:3], 0, v[12:13]
	global_store_dword v[12:13], v14, off sc1
	s_waitcnt lgkmcnt(0)
	v_fmac_f32_e32 v10, v14, v14
	s_waitcnt lgkmcnt(0)
	s_nop 0
	v_add_f32_dpp v10, v10, v10 quad_perm:[2,3,0,1] row_mask:0xf bank_mask:0xf
	s_waitcnt lgkmcnt(0)
	s_nop 0
	v_add_f32_dpp v10, v10, v10 row_half_mirror row_mask:0xf bank_mask:0xf
	s_waitcnt lgkmcnt(0)
	s_nop 0
	v_add_f32_dpp v10, v10, v10 row_mirror row_mask:0xf bank_mask:0xf
	v_mov_b32_e32 v11, v10
	s_nop 1
	v_permlane16_swap_b32_e32 v11, v10
	s_and_saveexec_b64 s[2:3], vcc
	s_cbranch_execz .LBB0_971
	s_waitcnt lgkmcnt(0)
	v_add_f32_e32 v12, v10, v11
	v_lshlrev_b64 v[10:11], 7, v[148:149]
	v_lshl_add_u64 v[10:11], s[0:1], 0, v[10:11]
	global_store_dword v[10:11], v12, off sc1
.LBB0_971:
	s_or_b64 exec, exec, s[2:3]
	s_waitcnt lgkmcnt(0)
	ds_read2st64_b32 v[10:11], v6 offset0:47 offset1:79
	ds_read_b32 v6, v6 offset:28416
	ds_read_b32 v12, v185 offset:3840
	s_waitcnt lgkmcnt(0)
	v_mov_b32_e32 v13, v11
	s_waitcnt lgkmcnt(0)
	v_mov_b32_e32 v11, v6
	s_waitcnt lgkmcnt(0)
	v_pk_add_f32 v[10:11], v[12:13], v[10:11]
	s_nop 0
	v_add_f32_e32 v6, v10, v11
	v_add_f32_e32 v10, v147, v6
	v_mul_f32_e32 v6, v10, v10
	s_nop 1
	v_mov_b32_dpp v4, v6 quad_perm:[1,0,3,2] row_mask:0xf bank_mask:0xf
	v_ashrrev_i32_e32 v147, 31, v146
	s_waitcnt lgkmcnt(0)
	v_fmac_f32_e32 v4, v10, v10
	s_waitcnt lgkmcnt(0)
	s_nop 0
	v_add_f32_dpp v4, v4, v4 quad_perm:[2,3,0,1] row_mask:0xf bank_mask:0xf
	v_lshlrev_b64 v[6:7], 12, v[146:147]
	v_lshl_add_u64 v[2:3], v[2:3], 0, v[6:7]
	global_store_dword v[2:3], v10, off sc1
	s_waitcnt lgkmcnt(0)
	v_add_f32_dpp v4, v4, v4 row_half_mirror row_mask:0xf bank_mask:0xf
	s_waitcnt lgkmcnt(0)
	s_nop 0
	v_add_f32_dpp v4, v4, v4 row_mirror row_mask:0xf bank_mask:0xf
	v_mov_b32_e32 v5, v4
	s_nop 1
	v_permlane16_swap_b32_e32 v5, v4
	s_and_saveexec_b64 s[2:3], vcc
	s_cbranch_execz .LBB0_973
	v_lshlrev_b64 v[2:3], 7, v[146:147]
	s_waitcnt lgkmcnt(0)
	v_add_f32_e32 v4, v4, v5
	v_lshl_add_u64 v[2:3], s[0:1], 0, v[2:3]
	global_store_dword v[2:3], v4, off sc1

;     DI void fused(f32x4 (&acc)[2][2][4][2], const pg8::Unit& u, int wr, int wc, int fr, int fq, LAS unsigned char* lds, int wid, int lane) const {
;     ...
; #pragma unroll
;         for (int ai = 0; ai < 2; ++ai)
; #pragma unroll
;             for (int m = 0; m < 4; ++m) {
;                 float ss = 0.f;
; #pragma unroll
;                 for (int bj = 0; bj < 2; ++bj) {
;                     const f32x4 v0 = acc[ai][bj][m][0], v1 = acc[ai][bj][m][1];
;                     ss += (v0[0] * v0[0] + v0[1] * v0[1]) + (v0[2] * v0[2] + v0[3] * v0[3]) + (v1[0] * v1[0] + v1[1] * v1[1]) + (v1[2] * v1[2] + v1[3] * v1[3]); }
;                 ss += __shfl_xor(ss, 16); ss += __shfl_xor(ss, 32);
;                 if (fq == 0) P[(ai * 128 + wr * 64 + m * 16 + fr) * 4 + wc] = ss; }
.LBB0_984:
	v_mbcnt_hi_u32_b32 v151, -1, v183
	v_and_b32_e32 v1, 64, v151
	v_xor_b32_e32 v0, 16, v151
	v_add_u32_e32 v153, 64, v1
	v_cmp_lt_i32_e32 vcc, v0, v153
	v_mul_f32_e32 v1, v81, v81
	v_fmac_f32_e32 v1, v80, v80
	v_cndmask_b32_e32 v0, v151, v0, vcc
	v_lshlrev_b32_e32 v152, 2, v0
	v_mul_f32_e32 v0, v79, v79
	v_fmac_f32_e32 v0, v78, v78
	v_add_f32_e32 v0, v0, v1
	v_mul_f32_e32 v1, v75, v75
	v_fmac_f32_e32 v1, v74, v74
	v_add_f32_e32 v0, v0, v1
	v_mul_f32_e32 v1, v77, v77
	v_fmac_f32_e32 v1, v76, v76
	v_add_f32_e32 v0, v1, v0
	v_mul_f32_e32 v1, v71, v71
	v_mul_f32_e32 v2, v73, v73
	v_fmac_f32_e32 v1, v70, v70
	v_fmac_f32_e32 v2, v72, v72
	v_add_f32_e32 v1, v1, v2
	v_mul_f32_e32 v2, v67, v67
	v_fmac_f32_e32 v2, v66, v66
	v_add_f32_e32 v1, v1, v2
	v_mul_f32_e32 v2, v69, v69
	v_fmac_f32_e32 v2, v68, v68
	v_add_f32_e32 v1, v2, v1
	v_add_f32_e32 v0, v0, v1
	v_mov_b32_e32 v1, v0
	s_nop 1
	v_permlane16_swap_b32_e32 v1, v0
	v_xor_b32_e32 v2, 32, v151
	v_cmp_lt_i32_e32 vcc, v2, v153
	s_lshl_b32 s0, s22, 2
	s_add_i32 s0, s0, 0
	v_cndmask_b32_e32 v2, v151, v2, vcc
	v_lshlrev_b32_e32 v154, 2, v2
	s_waitcnt lgkmcnt(0)
	v_add_f32_e32 v1, v0, v1
	v_mov_b32_e32 v2, v1
	s_nop 1
	v_permlane32_swap_b32_e32 v2, v1
	v_cmp_gt_u32_e32 vcc, 16, v182
	v_lshl_add_u32 v0, v149, 4, s0
	s_barrier
	s_and_saveexec_b64 s[0:1], vcc
	s_cbranch_execz .LBB0_986
	s_waitcnt lgkmcnt(0)
	v_add_f32_e32 v1, v1, v2
	ds_write_b32 v0, v1
.LBB0_986:
	s_or_b64 exec, exec, s[0:1]
	v_mul_f32_e32 v1, v63, v63
	s_waitcnt lgkmcnt(0)
	v_mul_f32_e32 v2, v65, v65
	v_fmac_f32_e32 v1, v62, v62
	v_fmac_f32_e32 v2, v64, v64
	v_add_f32_e32 v1, v1, v2
	v_mul_f32_e32 v2, v59, v59
	v_fmac_f32_e32 v2, v58, v58
	v_add_f32_e32 v1, v1, v2
	v_mul_f32_e32 v2, v61, v61
	v_fmac_f32_e32 v2, v60, v60
	v_add_f32_e32 v1, v2, v1
	v_mul_f32_e32 v2, v55, v55
	v_mul_f32_e32 v3, v57, v57
	v_fmac_f32_e32 v2, v54, v54
	v_fmac_f32_e32 v3, v56, v56
	v_add_f32_e32 v2, v2, v3
	v_mul_f32_e32 v3, v51, v51
	v_fmac_f32_e32 v3, v50, v50
	v_add_f32_e32 v2, v2, v3
	v_mul_f32_e32 v3, v53, v53
	v_fmac_f32_e32 v3, v52, v52
	v_add_f32_e32 v2, v3, v2
	v_add_f32_e32 v1, v1, v2
	v_mov_b32_e32 v2, v1
	s_nop 1
	v_permlane16_swap_b32_e32 v2, v1
	s_waitcnt lgkmcnt(0)
	v_add_f32_e32 v1, v1, v2
	v_mov_b32_e32 v2, v1
	s_nop 1
	v_permlane32_swap_b32_e32 v2, v1
	s_and_saveexec_b64 s[0:1], vcc
	s_cbranch_execz .LBB0_988
	s_waitcnt lgkmcnt(0)
	v_add_f32_e32 v1, v1, v2
	ds_write_b32 v0, v1 offset:256
.LBB0_988:
	s_or_b64 exec, exec, s[0:1]
	v_mul_f32_e32 v1, v47, v47
	s_waitcnt lgkmcnt(0)
	v_mul_f32_e32 v2, v49, v49
	v_fmac_f32_e32 v1, v46, v46
	v_fmac_f32_e32 v2, v48, v48
	v_add_f32_e32 v1, v1, v2
	v_mul_f32_e32 v2, v43, v43
	v_fmac_f32_e32 v2, v42, v42
	v_add_f32_e32 v1, v1, v2
	v_mul_f32_e32 v2, v45, v45
	v_fmac_f32_e32 v2, v44, v44
	v_add_f32_e32 v1, v2, v1
	v_mul_f32_e32 v2, v39, v39
	v_mul_f32_e32 v3, v41, v41
	v_fmac_f32_e32 v2, v38, v38
	v_fmac_f32_e32 v3, v40, v40
	v_add_f32_e32 v2, v2, v3
	v_mul_f32_e32 v3, v35, v35
	v_fmac_f32_e32 v3, v34, v34
	v_add_f32_e32 v2, v2, v3
	v_mul_f32_e32 v3, v37, v37
	v_fmac_f32_e32 v3, v36, v36
	v_add_f32_e32 v2, v3, v2
	v_add_f32_e32 v1, v1, v2
	v_mov_b32_e32 v2, v1
	s_nop 1
	v_permlane16_swap_b32_e32 v2, v1
	s_waitcnt lgkmcnt(0)
	v_add_f32_e32 v1, v1, v2
	v_mov_b32_e32 v2, v1
	s_nop 1
	v_permlane32_swap_b32_e32 v2, v1
	s_and_saveexec_b64 s[0:1], vcc
	s_cbranch_execz .LBB0_990
	s_waitcnt lgkmcnt(0)
	v_add_f32_e32 v1, v1, v2
	ds_write_b32 v0, v1 offset:512
.LBB0_990:
	s_or_b64 exec, exec, s[0:1]
	v_mul_f32_e32 v1, v31, v31
	s_waitcnt lgkmcnt(0)
	v_mul_f32_e32 v2, v33, v33
	v_fmac_f32_e32 v1, v30, v30
	v_fmac_f32_e32 v2, v32, v32
	v_add_f32_e32 v1, v1, v2
	v_mul_f32_e32 v2, v27, v27
	v_fmac_f32_e32 v2, v26, v26
	v_add_f32_e32 v1, v1, v2
	v_mul_f32_e32 v2, v29, v29
	v_fmac_f32_e32 v2, v28, v28
	v_add_f32_e32 v1, v2, v1
	v_mul_f32_e32 v2, v23, v23
	v_mul_f32_e32 v3, v25, v25
	v_fmac_f32_e32 v2, v22, v22
	v_fmac_f32_e32 v3, v24, v24
	v_add_f32_e32 v2, v2, v3
	v_mul_f32_e32 v3, v19, v19
	v_fmac_f32_e32 v3, v18, v18
	v_add_f32_e32 v2, v2, v3
	v_mul_f32_e32 v3, v21, v21
	v_fmac_f32_e32 v3, v20, v20
	v_add_f32_e32 v2, v3, v2
	v_add_f32_e32 v1, v1, v2
	v_mov_b32_e32 v2, v1
	s_nop 1
	v_permlane16_swap_b32_e32 v2, v1
	s_waitcnt lgkmcnt(0)
	v_add_f32_e32 v1, v1, v2
	v_mov_b32_e32 v2, v1
	s_nop 1
	v_permlane32_swap_b32_e32 v2, v1
	s_and_saveexec_b64 s[0:1], vcc
	s_cbranch_execz .LBB0_992
	s_waitcnt lgkmcnt(0)
	v_add_f32_e32 v1, v1, v2
	ds_write_b32 v0, v1 offset:768
;     DI void fused(f32x4 (&acc)[2][2][4][2], const pg8::Unit& u, int wr, int wc, int fr, int fq, LAS unsigned char* lds, int wid, int lane) const {
;     ...
; #pragma unroll
;         for (int ai = 0; ai < 2; ++ai)
; #pragma unroll
;             for (int m = 0; m < 4; ++m) {
;                 float ss = 0.f;
; #pragma unroll
;                 for (int bj = 0; bj < 2; ++bj) {
;                     const f32x4 v0 = acc[ai][bj][m][0], v1 = acc[ai][bj][m][1];
;                     ss += (v0[0] * v0[0] + v0[1] * v0[1]) + (v0[2] * v0[2] + v0[3] * v0[3]) + (v1[0] * v1[0] + v1[1] * v1[1]) + (v1[2] * v1[2] + v1[3] * v1[3]); }
;                 ss += __shfl_xor(ss, 16); ss += __shfl_xor(ss, 32);
;                 if (fq == 0) P[(ai * 128 + wr * 64 + m * 16 + fr) * 4 + wc] = ss; }
.LBB0_992:
	s_or_b64 exec, exec, s[0:1]
	v_mul_f32_e32 v1, v143, v143
	s_waitcnt lgkmcnt(0)
	v_mul_f32_e32 v2, v145, v145
	v_fmac_f32_e32 v1, v142, v142
	v_fmac_f32_e32 v2, v144, v144
	v_add_f32_e32 v1, v1, v2
	v_mul_f32_e32 v2, v139, v139
	v_fmac_f32_e32 v2, v138, v138
	v_add_f32_e32 v1, v1, v2
	v_mul_f32_e32 v2, v141, v141
	v_fmac_f32_e32 v2, v140, v140
	v_add_f32_e32 v1, v2, v1
	v_mul_f32_e32 v2, v135, v135
	v_mul_f32_e32 v3, v137, v137
	v_fmac_f32_e32 v2, v134, v134
	v_fmac_f32_e32 v3, v136, v136
	v_add_f32_e32 v2, v2, v3
	v_mul_f32_e32 v3, v131, v131
	v_fmac_f32_e32 v3, v130, v130
	v_add_f32_e32 v2, v2, v3
	v_mul_f32_e32 v3, v133, v133
	v_fmac_f32_e32 v3, v132, v132
	v_add_f32_e32 v2, v3, v2
	v_add_f32_e32 v1, v1, v2
	v_mov_b32_e32 v2, v1
	s_nop 1
	v_permlane16_swap_b32_e32 v2, v1
	s_waitcnt lgkmcnt(0)
	v_add_f32_e32 v1, v1, v2
	v_mov_b32_e32 v2, v1
	s_nop 1
	v_permlane32_swap_b32_e32 v2, v1
	s_and_saveexec_b64 s[0:1], vcc
	s_cbranch_execz .LBB0_994
	s_waitcnt lgkmcnt(0)
	v_add_f32_e32 v1, v1, v2
	ds_write_b32 v0, v1 offset:2048
.LBB0_994:
	s_or_b64 exec, exec, s[0:1]
	v_mul_f32_e32 v1, v127, v127
	s_waitcnt lgkmcnt(0)
	v_mul_f32_e32 v2, v129, v129
	v_fmac_f32_e32 v1, v126, v126
	v_fmac_f32_e32 v2, v128, v128
	v_add_f32_e32 v1, v1, v2
	v_mul_f32_e32 v2, v123, v123
	v_fmac_f32_e32 v2, v122, v122
	v_add_f32_e32 v1, v1, v2
	v_mul_f32_e32 v2, v125, v125
	v_fmac_f32_e32 v2, v124, v124
	v_add_f32_e32 v1, v2, v1
	v_mul_f32_e32 v2, v119, v119
	v_mul_f32_e32 v3, v121, v121
	v_fmac_f32_e32 v2, v118, v118
	v_fmac_f32_e32 v3, v120, v120
	v_add_f32_e32 v2, v2, v3
	v_mul_f32_e32 v3, v115, v115
	v_fmac_f32_e32 v3, v114, v114
	v_add_f32_e32 v2, v2, v3
	v_mul_f32_e32 v3, v117, v117
	v_fmac_f32_e32 v3, v116, v116
	v_add_f32_e32 v2, v3, v2
	v_add_f32_e32 v1, v1, v2
	v_mov_b32_e32 v2, v1
	s_nop 1
	v_permlane16_swap_b32_e32 v2, v1
	s_waitcnt lgkmcnt(0)
	v_add_f32_e32 v1, v1, v2
	v_mov_b32_e32 v2, v1
	s_nop 1
	v_permlane32_swap_b32_e32 v2, v1
	s_and_saveexec_b64 s[0:1], vcc
	s_cbranch_execz .LBB0_996
	s_waitcnt lgkmcnt(0)
	v_add_f32_e32 v1, v1, v2
	ds_write_b32 v0, v1 offset:2304
.LBB0_996:
	s_or_b64 exec, exec, s[0:1]
	v_mul_f32_e32 v1, v111, v111
	s_waitcnt lgkmcnt(0)
	v_mul_f32_e32 v2, v113, v113
	v_fmac_f32_e32 v1, v110, v110
	v_fmac_f32_e32 v2, v112, v112
	v_add_f32_e32 v1, v1, v2
	v_mul_f32_e32 v2, v107, v107
	v_fmac_f32_e32 v2, v106, v106
	v_add_f32_e32 v1, v1, v2
	v_mul_f32_e32 v2, v109, v109
	v_fmac_f32_e32 v2, v108, v108
	v_add_f32_e32 v1, v2, v1
	v_mul_f32_e32 v2, v103, v103
	v_mul_f32_e32 v3, v105, v105
	v_fmac_f32_e32 v2, v102, v102
	v_fmac_f32_e32 v3, v104, v104
	v_add_f32_e32 v2, v2, v3
	v_mul_f32_e32 v3, v99, v99
	v_fmac_f32_e32 v3, v98, v98
	v_add_f32_e32 v2, v2, v3
	v_mul_f32_e32 v3, v101, v101
	v_fmac_f32_e32 v3, v100, v100
	v_add_f32_e32 v2, v3, v2
	v_add_f32_e32 v1, v1, v2
	v_mov_b32_e32 v2, v1
	s_nop 1
	v_permlane16_swap_b32_e32 v2, v1
	s_waitcnt lgkmcnt(0)
	v_add_f32_e32 v1, v1, v2
	v_mov_b32_e32 v2, v1
	s_nop 1
	v_permlane32_swap_b32_e32 v2, v1
	s_and_saveexec_b64 s[0:1], vcc
	s_cbranch_execz .LBB0_998
	s_waitcnt lgkmcnt(0)
	v_add_f32_e32 v1, v1, v2
	ds_write_b32 v0, v1 offset:2560
.LBB0_998:
	s_or_b64 exec, exec, s[0:1]
	v_mul_f32_e32 v1, v95, v95
	s_waitcnt lgkmcnt(0)
	v_mul_f32_e32 v2, v97, v97
	v_fmac_f32_e32 v1, v94, v94
	v_fmac_f32_e32 v2, v96, v96
	v_add_f32_e32 v1, v1, v2
	v_mul_f32_e32 v2, v91, v91
	v_fmac_f32_e32 v2, v90, v90
	v_add_f32_e32 v1, v1, v2
	v_mul_f32_e32 v2, v93, v93
	v_fmac_f32_e32 v2, v92, v92
	v_add_f32_e32 v1, v2, v1
	v_mul_f32_e32 v2, v87, v87
	v_mul_f32_e32 v3, v89, v89
	v_fmac_f32_e32 v2, v86, v86
	v_fmac_f32_e32 v3, v88, v88
	v_add_f32_e32 v2, v2, v3
	v_mul_f32_e32 v3, v83, v83
	v_fmac_f32_e32 v3, v82, v82
	v_add_f32_e32 v2, v2, v3
	v_mul_f32_e32 v3, v85, v85
	v_fmac_f32_e32 v3, v84, v84
	v_add_f32_e32 v2, v3, v2
	v_add_f32_e32 v1, v1, v2
	v_mov_b32_e32 v2, v1
	s_nop 1
	v_permlane16_swap_b32_e32 v2, v1
	s_waitcnt lgkmcnt(0)
	v_add_f32_e32 v1, v1, v2
	v_mov_b32_e32 v2, v1
	s_nop 1
	v_permlane32_swap_b32_e32 v2, v1
	s_and_saveexec_b64 s[0:1], vcc
	s_cbranch_execz .LBB0_1000
	s_waitcnt lgkmcnt(0)
	v_add_f32_e32 v1, v1, v2
	ds_write_b32 v0, v1 offset:2816
